# best3 + nt on pool ZA/gate fetches and GLU epilogue YG/gc loads
# speedup vs baseline: 1.0225x; 1.0070x over previous
; __device__ __forceinline__ float sigm(float v) { return __builtin_amdgcn_rcpf(1.0f + __builtin_amdgcn_exp2f(-LOG2E * v)); }
; __device__ __forceinline__ float bf_lo(unsigned w) { return __uint_as_float(w << 16); }
; __device__ __forceinline__ float silu_f(float v) { return v * __builtin_amdgcn_rcpf(1.0f + __builtin_amdgcn_exp2f(-1.4426950408889634f * v)); }
;     __device__ __forceinline__ void operator()(const f32x4 (&acc)[2][2][4][2], const Unit& u, int wr, int wc, int fr, int fq) const {
;         EPI_LANE();
;         const char* ygb = (const char*)(YG + (size_t)u.pm * BM * 256); const char* sgb = (const char*)(ZC + (size_t)u.pm * BM * 512 + 256); char* yb = (char*)(Y + (size_t)u.pm * BM * 1024 + 768);
;         unsigned rl0 = (unsigned)(wr * 64 + fr), col0 = (unsigned)(wc * 32 + 8 * fq); asm volatile("" : "+v"(rl0), "+v"(col0));
; #pragma unroll
;         for (int bj = 0; bj < 2; ++bj) { const unsigned col = col0 + bj * HALF;
; #pragma unroll
;             for (int ai = 0; ai < 2; ++ai) {
;                 u32x4 ygv[4], sgv[4];
; #pragma unroll
;                 for (int m = 0; m < 4; ++m) { const unsigned rl = rl0 + (unsigned)(ai * HALF + m * 16);
;                     ygv[m] = *(const u32x4*)(ygb + (rl * 256u + col) * 2u); sgv[m] = *(const u32x4*)(sgb + (rl * 512u + col) * 2u); }
; #pragma unroll
;                 for (int m = 0; m < 4; ++m) { const unsigned rl = rl0 + (unsigned)(ai * HALF + m * 16);
;                     const u32x4 yg = ygv[m], sg = sgv[m];
;                     const f32x4 v0 = acc[ai][bj][m][0], v1 = acc[ai][bj][m][1];
;                     u32x4 w;
;                     w.x = cvt_pk_bf16(bf_lo(yg.x) * sigm(v0[0]) * silu_f(bf_lo(sg.x)), bf_hi(yg.x) * sigm(v0[1]) * silu_f(bf_hi(sg.x)));
;                     w.y = cvt_pk_bf16(bf_lo(yg.y) * sigm(v0[2]) * silu_f(bf_lo(sg.y)), bf_hi(yg.y) * sigm(v0[3]) * silu_f(bf_hi(sg.y)));
;                     w.z = cvt_pk_bf16(bf_lo(yg.z) * sigm(v1[0]) * silu_f(bf_lo(sg.z)), bf_hi(yg.z) * sigm(v1[1]) * silu_f(bf_hi(sg.z)));
;                     w.w = cvt_pk_bf16(bf_lo(yg.w) * sigm(v1[2]) * silu_f(bf_lo(sg.w)), bf_hi(yg.w) * sigm(v1[3]) * silu_f(bf_hi(sg.w)));
;                     *(u32x4*)(yb + (rl * 1024u + col) * 2u) = w; }
;                 asm volatile("" : "+v"(rl0), "+v"(col0) :: "memory"); } }
;     }
.LBB0_82:
	v_readlane_b32 s20, v253, 0
	v_readlane_b32 s21, v253, 1
	s_load_dwordx4 s[76:79], s[20:21], 0xa8
	s_ashr_i32 s61, s60, 31
	s_lshl_b64 s[16:17], s[60:61], 17
	s_add_u32 s62, s90, s16
	s_addc_u32 s63, s91, s17
	s_lshl_b64 s[16:17], s[60:61], 18
	s_waitcnt lgkmcnt(0)
	s_add_u32 s6, s78, s16
	s_addc_u32 s12, s79, s17
	s_add_u32 s64, s6, 0xc000200
	v_mov_b32_e32 v106, v212
	s_addc_u32 s65, s12, 0
	s_lshl_b64 s[16:17], s[60:61], 19
	s_add_u32 s60, s82, s16
	v_readfirstlane_b32 s0, v106
	s_addc_u32 s61, s83, s17
	s_ashr_i32 s6, s0, 2
	s_andn2_b32 s6, s6, 63
	s_lshr_b32 s0, s0, 1
	v_and_or_b32 v174, v106, 15, s6
	s_and_b32 s0, s0, 0x60
	v_lshrrev_b32_e32 v106, 1, v106
	v_and_or_b32 v175, v106, 24, s0
	v_mul_f32_e32 v158, 0xbfb8aa3b, v158
	v_lshlrev_b32_e32 v176, 1, v175
	v_lshlrev_b32_e32 v106, 9, v174
	v_add_u32_e32 v107, v106, v176
	v_add_u32_e32 v177, v107, v106
	global_load_dwordx4 v[150:153], v107, s[62:63] nt
	global_load_dwordx4 v[154:157], v177, s[64:65] nt
	v_add_u32_e32 v107, 0x2000, v106
	v_add_u32_e32 v108, v107, v176
	v_add_u32_e32 v107, v108, v107
	global_load_dwordx4 v[138:141], v108, s[62:63] nt
	global_load_dwordx4 v[142:145], v107, s[64:65] nt
	v_mul_f32_e32 v159, 0xbfb8aa3b, v159
	v_exp_f32_e32 v158, v158
	v_exp_f32_e32 v159, v159
	v_mul_f32_e32 v146, 0xbfb8aa3b, v146
	v_mul_f32_e32 v147, 0xbfb8aa3b, v147
	v_add_f32_e32 v158, 1.0, v158
	v_add_f32_e32 v159, 1.0, v159
	v_rcp_f32_e32 v158, v158
	v_rcp_f32_e32 v159, v159
	v_exp_f32_e32 v146, v146
	v_exp_f32_e32 v147, v147
	v_add_u32_e32 v107, 0x4000, v106
	v_add_u32_e32 v108, v107, v176
	v_add_f32_e32 v146, 1.0, v146
	v_add_f32_e32 v147, 1.0, v147
	v_rcp_f32_e32 v146, v146
	v_rcp_f32_e32 v147, v147
	v_add_u32_e32 v107, v108, v107
	global_load_dwordx4 v[122:125], v108, s[62:63] nt
	global_load_dwordx4 v[126:129], v107, s[64:65] nt
	v_add_u32_e32 v110, 0x6000, v106
	v_add_u32_e32 v111, v110, v176
	v_add_u32_e32 v110, v111, v110
	global_load_dwordx4 v[106:109], v111, s[62:63] nt
	v_mul_f32_e32 v134, 0xbfb8aa3b, v134
	global_load_dwordx4 v[110:113], v110, s[64:65] nt
	v_mul_f32_e32 v135, 0xbfb8aa3b, v135
	v_exp_f32_e32 v134, v134
	v_exp_f32_e32 v135, v135
	v_mul_f32_e32 v130, 0xbfb8aa3b, v130
	v_mul_f32_e32 v131, 0xbfb8aa3b, v131
	v_add_f32_e32 v134, 1.0, v134
	v_add_f32_e32 v135, 1.0, v135
	v_rcp_f32_e32 v134, v134
	v_rcp_f32_e32 v135, v135
	v_exp_f32_e32 v130, v130
	v_exp_f32_e32 v131, v131
	v_mul_f32_e32 v118, 0xbfb8aa3b, v118
	v_mul_f32_e32 v119, 0xbfb8aa3b, v119
	v_add_f32_e32 v130, 1.0, v130
	v_add_f32_e32 v131, 1.0, v131
	v_rcp_f32_e32 v130, v130
	v_rcp_f32_e32 v131, v131
	v_exp_f32_e32 v118, v118
	v_exp_f32_e32 v119, v119
	v_mul_f32_e32 v114, 0xbfb8aa3b, v114
	v_mul_f32_e32 v115, 0xbfb8aa3b, v115
	v_add_f32_e32 v118, 1.0, v118
	v_add_f32_e32 v119, 1.0, v119
	v_rcp_f32_e32 v118, v118
	v_rcp_f32_e32 v119, v119
	v_exp_f32_e32 v114, v114
	v_exp_f32_e32 v115, v115
	v_mul_f32_e32 v102, 0xbfb8aa3b, v102
	v_mul_f32_e32 v103, 0xbfb8aa3b, v103
	v_add_f32_e32 v114, 1.0, v114
	v_add_f32_e32 v115, 1.0, v115
	v_rcp_f32_e32 v114, v114
	v_rcp_f32_e32 v115, v115
	v_exp_f32_e32 v102, v102
	v_exp_f32_e32 v103, v103
	v_mul_f32_e32 v98, 0xbfb8aa3b, v98
	v_mul_f32_e32 v99, 0xbfb8aa3b, v99
	v_add_f32_e32 v102, 1.0, v102
	v_add_f32_e32 v103, 1.0, v103
	v_rcp_f32_e32 v102, v102
	v_rcp_f32_e32 v103, v103
	v_exp_f32_e32 v98, v98
	v_exp_f32_e32 v99, v99
	v_mul_f32_e32 v92, 0xbfb8aa3b, v92
	v_mul_f32_e32 v93, 0xbfb8aa3b, v93
	v_add_f32_e32 v98, 1.0, v98
	v_add_f32_e32 v99, 1.0, v99
	s_waitcnt vmcnt(0)
	v_lshlrev_b32_e32 v182, 16, v150
	v_lshlrev_b32_e32 v178, 16, v154
	v_and_b32_e32 v179, 0xffff0000, v154
	v_mul_f32_e32 v154, 0xbfb8aa3b, v178
	v_and_b32_e32 v183, 0xffff0000, v150
	v_mul_f32_e32 v150, 0xbfb8aa3b, v179
	v_exp_f32_e32 v154, v154
	v_exp_f32_e32 v150, v150
	v_pk_mul_f32 v[158:159], v[158:159], v[182:183]
	v_rcp_f32_e32 v98, v98
	v_add_f32_e32 v154, 1.0, v154
	v_add_f32_e32 v150, 1.0, v150
	v_rcp_f32_e32 v180, v154
	v_rcp_f32_e32 v181, v150
	v_mul_f32_e32 v154, 0xbfb8aa3b, v160
	v_exp_f32_e32 v154, v154
	v_rcp_f32_e32 v99, v99
	v_pk_mul_f32 v[178:179], v[180:181], v[178:179]
	v_exp_f32_e32 v92, v92
	v_pk_mul_f32 v[158:159], v[158:159], v[178:179]
	v_add_f32_e32 v154, 1.0, v154
	v_cvt_pk_bf16_f32 v150, v158, v159
	v_rcp_f32_e32 v158, v154
	v_mul_f32_e32 v154, 0xbfb8aa3b, v161
	v_exp_f32_e32 v154, v154
	v_lshlrev_b32_e32 v178, 16, v151
	v_and_b32_e32 v179, 0xffff0000, v151
	v_exp_f32_e32 v93, v93
	v_add_f32_e32 v154, 1.0, v154
	v_rcp_f32_e32 v159, v154
	v_lshlrev_b32_e32 v154, 16, v155
	v_and_b32_e32 v155, 0xffff0000, v155
	v_mul_f32_e32 v160, 0xbfb8aa3b, v154
	v_mul_f32_e32 v151, 0xbfb8aa3b, v155
	v_exp_f32_e32 v160, v160
	v_exp_f32_e32 v151, v151
	v_pk_mul_f32 v[158:159], v[158:159], v[178:179]
	v_add_f32_e32 v92, 1.0, v92
	v_add_f32_e32 v160, 1.0, v160
	v_add_f32_e32 v151, 1.0, v151
	v_rcp_f32_e32 v160, v160
	v_rcp_f32_e32 v161, v151
	v_add_f32_e32 v93, 1.0, v93
	v_rcp_f32_e32 v92, v92
	v_rcp_f32_e32 v93, v93
	v_pk_mul_f32 v[154:155], v[160:161], v[154:155]
	v_lshlrev_b32_e32 v160, 16, v152
	v_pk_mul_f32 v[154:155], v[158:159], v[154:155]
	v_and_b32_e32 v161, 0xffff0000, v152
	v_cvt_pk_bf16_f32 v151, v154, v155
	v_lshlrev_b32_e32 v154, 16, v156
	v_and_b32_e32 v155, 0xffff0000, v156
	v_mul_f32_e32 v156, 0xbfb8aa3b, v154
	v_mul_f32_e32 v152, 0xbfb8aa3b, v155
	v_exp_f32_e32 v156, v156
	v_exp_f32_e32 v152, v152
	v_pk_mul_f32 v[146:147], v[146:147], v[160:161]
	v_mul_f32_e32 v88, 0xbfb8aa3b, v88
	v_add_f32_e32 v156, 1.0, v156
	v_add_f32_e32 v152, 1.0, v152
	v_rcp_f32_e32 v158, v156
	v_rcp_f32_e32 v159, v152
	v_lshlrev_b32_e32 v156, 16, v153
	v_mul_f32_e32 v89, 0xbfb8aa3b, v89
; __device__ __forceinline__ unsigned cvt_pk_bf16(float lo, float hi) { f32x2_t v = {lo, hi}; bf16x2_t b = __builtin_convertvector(v, bf16x2_t); return __builtin_bit_cast(unsigned, b); }
; __device__ __forceinline__ float sigm(float v) { return __builtin_amdgcn_rcpf(1.0f + __builtin_amdgcn_exp2f(-LOG2E * v)); }
; __device__ __forceinline__ float bf_lo(unsigned w) { return __uint_as_float(w << 16); }
; __device__ __forceinline__ float silu_f(float v) { return v * __builtin_amdgcn_rcpf(1.0f + __builtin_amdgcn_exp2f(-1.4426950408889634f * v)); }
; __device__ __forceinline__ float bf_hi(unsigned w) { return __uint_as_float(w & 0xffff0000u); }
;     __device__ __forceinline__ void operator()(const f32x4 (&acc)[2][2][4][2], const Unit& u, int wr, int wc, int fr, int fq) const {
;     ...
;                 for (int m = 0; m < 4; ++m) { const unsigned rl = rl0 + (unsigned)(ai * HALF + m * 16);
;                     const u32x4 yg = ygv[m], sg = sgv[m];
;                     const f32x4 v0 = acc[ai][bj][m][0], v1 = acc[ai][bj][m][1];
;                     u32x4 w;
;                     w.x = cvt_pk_bf16(bf_lo(yg.x) * sigm(v0[0]) * silu_f(bf_lo(sg.x)), bf_hi(yg.x) * sigm(v0[1]) * silu_f(bf_hi(sg.x)));
;                     w.y = cvt_pk_bf16(bf_lo(yg.y) * sigm(v0[2]) * silu_f(bf_lo(sg.y)), bf_hi(yg.y) * sigm(v0[3]) * silu_f(bf_hi(sg.y)));
;                     w.z = cvt_pk_bf16(bf_lo(yg.z) * sigm(v1[0]) * silu_f(bf_lo(sg.z)), bf_hi(yg.z) * sigm(v1[1]) * silu_f(bf_hi(sg.z)));
;                     w.w = cvt_pk_bf16(bf_lo(yg.w) * sigm(v1[2]) * silu_f(bf_lo(sg.w)), bf_hi(yg.w) * sigm(v1[3]) * silu_f(bf_hi(sg.w)));
;                     *(u32x4*)(yb + (rl * 1024u + col) * 2u) = w; }
	v_exp_f32_e32 v88, v88
	v_pk_mul_f32 v[154:155], v[158:159], v[154:155]
	v_exp_f32_e32 v89, v89
	v_pk_mul_f32 v[146:147], v[146:147], v[154:155]
	v_add_f32_e32 v88, 1.0, v88
	v_cvt_pk_bf16_f32 v152, v146, v147
	v_mul_f32_e32 v146, 0xbfb8aa3b, v148
	v_mul_f32_e32 v147, 0xbfb8aa3b, v149
	v_lshlrev_b32_e32 v148, 16, v157
	v_and_b32_e32 v149, 0xffff0000, v157
	v_mul_f32_e32 v154, 0xbfb8aa3b, v148
	v_and_b32_e32 v157, 0xffff0000, v153
	v_mul_f32_e32 v153, 0xbfb8aa3b, v149
	v_exp_f32_e32 v146, v146
	v_exp_f32_e32 v147, v147
	v_exp_f32_e32 v154, v154
	v_exp_f32_e32 v153, v153
	v_add_f32_e32 v146, 1.0, v146
	v_add_f32_e32 v147, 1.0, v147
	v_add_f32_e32 v154, 1.0, v154
	v_add_f32_e32 v153, 1.0, v153
	v_rcp_f32_e32 v146, v146
	v_rcp_f32_e32 v147, v147
	v_rcp_f32_e32 v154, v154
	v_rcp_f32_e32 v155, v153
	v_add_f32_e32 v89, 1.0, v89
	v_pk_mul_f32 v[146:147], v[146:147], v[156:157]
	v_rcp_f32_e32 v88, v88
	v_pk_mul_f32 v[148:149], v[154:155], v[148:149]
	v_rcp_f32_e32 v89, v89
	v_pk_mul_f32 v[146:147], v[146:147], v[148:149]
	v_lshlrev_b32_e32 v148, 16, v142
	v_cvt_pk_bf16_f32 v153, v146, v147
	v_lshl_add_u32 v146, v174, 10, v177
	v_and_b32_e32 v149, 0xffff0000, v142
	global_store_dwordx4 v146, v[150:153], s[60:61] offset:1536
	v_mul_f32_e32 v142, 0xbfb8aa3b, v148
	v_exp_f32_e32 v142, v142
	v_lshlrev_b32_e32 v152, 16, v138
	v_and_b32_e32 v153, 0xffff0000, v138
	v_mul_f32_e32 v138, 0xbfb8aa3b, v149
	v_exp_f32_e32 v138, v138
	v_add_f32_e32 v142, 1.0, v142
	v_rcp_f32_e32 v150, v142
	v_pk_mul_f32 v[134:135], v[134:135], v[152:153]
	v_add_f32_e32 v138, 1.0, v138
	v_rcp_f32_e32 v151, v138
	v_lshlrev_b32_e32 v142, 16, v143
	v_and_b32_e32 v143, 0xffff0000, v143
	v_mul_f32_e32 v84, 0xbfb8aa3b, v84
	v_pk_mul_f32 v[148:149], v[150:151], v[148:149]
	v_mul_f32_e32 v85, 0xbfb8aa3b, v85
	v_pk_mul_f32 v[134:135], v[134:135], v[148:149]
	v_lshlrev_b32_e32 v148, 16, v139
	v_cvt_pk_bf16_f32 v134, v134, v135
	v_mul_f32_e32 v135, 0xbfb8aa3b, v136
	v_exp_f32_e32 v135, v135
	v_and_b32_e32 v149, 0xffff0000, v139
	v_exp_f32_e32 v84, v84
	v_exp_f32_e32 v85, v85
	v_add_f32_e32 v135, 1.0, v135
	v_rcp_f32_e32 v136, v135
	v_mul_f32_e32 v135, 0xbfb8aa3b, v137
	v_exp_f32_e32 v135, v135
	v_add_f32_e32 v84, 1.0, v84
	v_add_f32_e32 v85, 1.0, v85
	v_rcp_f32_e32 v84, v84
	v_add_f32_e32 v135, 1.0, v135
	v_rcp_f32_e32 v137, v135
	v_mul_f32_e32 v135, 0xbfb8aa3b, v142
	v_exp_f32_e32 v135, v135
	v_rcp_f32_e32 v85, v85
	v_pk_mul_f32 v[136:137], v[136:137], v[148:149]
	v_mul_f32_e32 v80, 0xbfb8aa3b, v80
	v_add_f32_e32 v135, 1.0, v135
	v_rcp_f32_e32 v138, v135
	v_mul_f32_e32 v135, 0xbfb8aa3b, v143
	v_exp_f32_e32 v135, v135
	v_mul_f32_e32 v81, 0xbfb8aa3b, v81
	v_exp_f32_e32 v80, v80
	v_exp_f32_e32 v81, v81
	v_add_f32_e32 v135, 1.0, v135
	v_rcp_f32_e32 v139, v135
	v_add_f32_e32 v80, 1.0, v80
	v_add_f32_e32 v81, 1.0, v81
	v_rcp_f32_e32 v80, v80
	v_pk_mul_f32 v[138:139], v[138:139], v[142:143]
	v_lshlrev_b32_e32 v142, 16, v140
	v_pk_mul_f32 v[136:137], v[136:137], v[138:139]
	v_and_b32_e32 v143, 0xffff0000, v140
	v_cvt_pk_bf16_f32 v135, v136, v137
	v_lshlrev_b32_e32 v136, 16, v144
	v_and_b32_e32 v137, 0xffff0000, v144
	v_mul_f32_e32 v138, 0xbfb8aa3b, v136
	v_mul_f32_e32 v139, 0xbfb8aa3b, v137
	v_exp_f32_e32 v138, v138
	v_exp_f32_e32 v139, v139
	v_pk_mul_f32 v[130:131], v[130:131], v[142:143]
	v_lshlrev_b32_e32 v140, 16, v141
	v_add_f32_e32 v138, 1.0, v138
	v_add_f32_e32 v139, 1.0, v139
	v_rcp_f32_e32 v138, v138
	v_rcp_f32_e32 v139, v139
	v_and_b32_e32 v141, 0xffff0000, v141
	v_rcp_f32_e32 v81, v81
	v_mul_f32_e32 v76, 0xbfb8aa3b, v76
	v_pk_mul_f32 v[136:137], v[138:139], v[136:137]
	v_mul_f32_e32 v77, 0xbfb8aa3b, v77
	v_pk_mul_f32 v[130:131], v[130:131], v[136:137]
	v_exp_f32_e32 v76, v76
	v_cvt_pk_bf16_f32 v136, v130, v131
	v_mul_f32_e32 v130, 0xbfb8aa3b, v132
	v_lshlrev_b32_e32 v132, 16, v145
	v_mul_f32_e32 v137, 0xbfb8aa3b, v132
	v_exp_f32_e32 v137, v137
	v_mul_f32_e32 v131, 0xbfb8aa3b, v133
	v_and_b32_e32 v133, 0xffff0000, v145
	v_exp_f32_e32 v130, v130
	v_add_f32_e32 v137, 1.0, v137
	v_rcp_f32_e32 v138, v137
	v_mul_f32_e32 v137, 0xbfb8aa3b, v133
	v_exp_f32_e32 v131, v131
	v_exp_f32_e32 v137, v137
	v_add_f32_e32 v130, 1.0, v130
	v_rcp_f32_e32 v130, v130
	v_add_f32_e32 v131, 1.0, v131
	v_add_f32_e32 v137, 1.0, v137
	v_rcp_f32_e32 v131, v131
	v_rcp_f32_e32 v139, v137
	v_exp_f32_e32 v77, v77
	v_add_f32_e32 v76, 1.0, v76
	v_pk_mul_f32 v[130:131], v[130:131], v[140:141]
	v_pk_mul_f32 v[132:133], v[138:139], v[132:133]
	v_add_f32_e32 v77, 1.0, v77
	v_pk_mul_f32 v[130:131], v[130:131], v[132:133]
	v_rcp_f32_e32 v76, v76
	v_cvt_pk_bf16_f32 v137, v130, v131
	v_add_u32_e32 v130, 0x8000, v146
	global_store_dwordx4 v130, v[134:137], s[60:61] offset:1536
	v_lshlrev_b32_e32 v130, 16, v126
	v_and_b32_e32 v131, 0xffff0000, v126
	v_mul_f32_e32 v126, 0xbfb8aa3b, v130
	v_lshlrev_b32_e32 v134, 16, v122
	v_and_b32_e32 v135, 0xffff0000, v122
	v_mul_f32_e32 v122, 0xbfb8aa3b, v131
	v_exp_f32_e32 v126, v126
	v_exp_f32_e32 v122, v122
	v_pk_mul_f32 v[118:119], v[118:119], v[134:135]
	v_rcp_f32_e32 v77, v77
	v_add_f32_e32 v126, 1.0, v126
	v_add_f32_e32 v122, 1.0, v122
	v_rcp_f32_e32 v132, v126
	v_rcp_f32_e32 v133, v122
	v_lshlrev_b32_e32 v126, 16, v127
	v_and_b32_e32 v127, 0xffff0000, v127
	v_mul_f32_e32 v72, 0xbfb8aa3b, v72
	v_pk_mul_f32 v[130:131], v[132:133], v[130:131]
	v_mul_f32_e32 v73, 0xbfb8aa3b, v73
	v_pk_mul_f32 v[118:119], v[118:119], v[130:131]
	v_lshlrev_b32_e32 v130, 16, v123
	v_cvt_pk_bf16_f32 v118, v118, v119
	v_mul_f32_e32 v119, 0xbfb8aa3b, v120
	v_exp_f32_e32 v119, v119
	v_and_b32_e32 v131, 0xffff0000, v123
	v_exp_f32_e32 v72, v72
	v_exp_f32_e32 v73, v73
	v_add_f32_e32 v119, 1.0, v119
	v_rcp_f32_e32 v120, v119
; __device__ __forceinline__ unsigned cvt_pk_bf16(float lo, float hi) { f32x2_t v = {lo, hi}; bf16x2_t b = __builtin_convertvector(v, bf16x2_t); return __builtin_bit_cast(unsigned, b); }
; __device__ __forceinline__ float sigm(float v) { return __builtin_amdgcn_rcpf(1.0f + __builtin_amdgcn_exp2f(-LOG2E * v)); }
; __device__ __forceinline__ float bf_lo(unsigned w) { return __uint_as_float(w << 16); }
; __device__ __forceinline__ float silu_f(float v) { return v * __builtin_amdgcn_rcpf(1.0f + __builtin_amdgcn_exp2f(-1.4426950408889634f * v)); }
; __device__ __forceinline__ float bf_hi(unsigned w) { return __uint_as_float(w & 0xffff0000u); }
;     __device__ __forceinline__ void operator()(const f32x4 (&acc)[2][2][4][2], const Unit& u, int wr, int wc, int fr, int fq) const {
;     ...
;                 for (int m = 0; m < 4; ++m) { const unsigned rl = rl0 + (unsigned)(ai * HALF + m * 16);
;                     const u32x4 yg = ygv[m], sg = sgv[m];
;                     const f32x4 v0 = acc[ai][bj][m][0], v1 = acc[ai][bj][m][1];
;                     u32x4 w;
;                     w.x = cvt_pk_bf16(bf_lo(yg.x) * sigm(v0[0]) * silu_f(bf_lo(sg.x)), bf_hi(yg.x) * sigm(v0[1]) * silu_f(bf_hi(sg.x)));
;                     w.y = cvt_pk_bf16(bf_lo(yg.y) * sigm(v0[2]) * silu_f(bf_lo(sg.y)), bf_hi(yg.y) * sigm(v0[3]) * silu_f(bf_hi(sg.y)));
;                     w.z = cvt_pk_bf16(bf_lo(yg.z) * sigm(v1[0]) * silu_f(bf_lo(sg.z)), bf_hi(yg.z) * sigm(v1[1]) * silu_f(bf_hi(sg.z)));
;                     w.w = cvt_pk_bf16(bf_lo(yg.w) * sigm(v1[2]) * silu_f(bf_lo(sg.w)), bf_hi(yg.w) * sigm(v1[3]) * silu_f(bf_hi(sg.w)));
;                     *(u32x4*)(yb + (rl * 1024u + col) * 2u) = w; }
	v_mul_f32_e32 v119, 0xbfb8aa3b, v121
	v_exp_f32_e32 v119, v119
	v_add_f32_e32 v72, 1.0, v72
	v_add_f32_e32 v73, 1.0, v73
	v_rcp_f32_e32 v72, v72
	v_add_f32_e32 v119, 1.0, v119
	v_rcp_f32_e32 v121, v119
	v_mul_f32_e32 v119, 0xbfb8aa3b, v126
	v_exp_f32_e32 v119, v119
	v_rcp_f32_e32 v73, v73
	v_pk_mul_f32 v[120:121], v[120:121], v[130:131]
	v_mul_f32_e32 v68, 0xbfb8aa3b, v68
	v_add_f32_e32 v119, 1.0, v119
	v_rcp_f32_e32 v122, v119
	v_mul_f32_e32 v119, 0xbfb8aa3b, v127
	v_exp_f32_e32 v119, v119
	v_mul_f32_e32 v69, 0xbfb8aa3b, v69
	v_exp_f32_e32 v68, v68
	v_exp_f32_e32 v69, v69
	v_add_f32_e32 v119, 1.0, v119
	v_rcp_f32_e32 v123, v119
	v_add_f32_e32 v68, 1.0, v68
	v_add_f32_e32 v69, 1.0, v69
	v_rcp_f32_e32 v68, v68
	v_pk_mul_f32 v[122:123], v[122:123], v[126:127]
	v_lshlrev_b32_e32 v126, 16, v124
	v_pk_mul_f32 v[120:121], v[120:121], v[122:123]
	v_and_b32_e32 v127, 0xffff0000, v124
	v_cvt_pk_bf16_f32 v119, v120, v121
	v_lshlrev_b32_e32 v120, 16, v128
	v_and_b32_e32 v121, 0xffff0000, v128
	v_mul_f32_e32 v122, 0xbfb8aa3b, v120
	v_mul_f32_e32 v123, 0xbfb8aa3b, v121
	v_exp_f32_e32 v122, v122
	v_exp_f32_e32 v123, v123
	v_pk_mul_f32 v[114:115], v[114:115], v[126:127]
	v_lshlrev_b32_e32 v124, 16, v125
	v_add_f32_e32 v122, 1.0, v122
	v_add_f32_e32 v123, 1.0, v123
	v_rcp_f32_e32 v122, v122
	v_rcp_f32_e32 v123, v123
	v_and_b32_e32 v125, 0xffff0000, v125
	v_rcp_f32_e32 v69, v69
	v_mul_f32_e32 v60, 0xbfb8aa3b, v60
	v_pk_mul_f32 v[120:121], v[122:123], v[120:121]
	v_mul_f32_e32 v61, 0xbfb8aa3b, v61
	v_pk_mul_f32 v[114:115], v[114:115], v[120:121]
	v_exp_f32_e32 v60, v60
	v_cvt_pk_bf16_f32 v120, v114, v115
	v_mul_f32_e32 v114, 0xbfb8aa3b, v116
	v_lshlrev_b32_e32 v116, 16, v129
	v_mul_f32_e32 v121, 0xbfb8aa3b, v116
	v_exp_f32_e32 v121, v121
	v_mul_f32_e32 v115, 0xbfb8aa3b, v117
	v_and_b32_e32 v117, 0xffff0000, v129
	v_exp_f32_e32 v114, v114
	v_add_f32_e32 v121, 1.0, v121
	v_rcp_f32_e32 v122, v121
	v_mul_f32_e32 v121, 0xbfb8aa3b, v117
	v_exp_f32_e32 v115, v115
	v_exp_f32_e32 v121, v121
	v_add_f32_e32 v114, 1.0, v114
	v_rcp_f32_e32 v114, v114
	v_add_f32_e32 v115, 1.0, v115
	v_add_f32_e32 v121, 1.0, v121
	v_rcp_f32_e32 v115, v115
	v_rcp_f32_e32 v123, v121
	v_exp_f32_e32 v61, v61
	v_add_f32_e32 v60, 1.0, v60
	v_pk_mul_f32 v[114:115], v[114:115], v[124:125]
	v_pk_mul_f32 v[116:117], v[122:123], v[116:117]
	v_add_f32_e32 v61, 1.0, v61
	v_pk_mul_f32 v[114:115], v[114:115], v[116:117]
	v_rcp_f32_e32 v60, v60
	v_cvt_pk_bf16_f32 v121, v114, v115
	v_add_u32_e32 v114, 0x10000, v146
	global_store_dwordx4 v114, v[118:121], s[60:61] offset:1536
	v_lshlrev_b32_e32 v114, 16, v110
	v_and_b32_e32 v115, 0xffff0000, v110
	v_mul_f32_e32 v110, 0xbfb8aa3b, v114
	v_lshlrev_b32_e32 v118, 16, v106
	v_and_b32_e32 v119, 0xffff0000, v106
	v_mul_f32_e32 v106, 0xbfb8aa3b, v115
	v_exp_f32_e32 v110, v110
	v_exp_f32_e32 v106, v106
	v_pk_mul_f32 v[102:103], v[102:103], v[118:119]
	v_rcp_f32_e32 v61, v61
	v_add_f32_e32 v110, 1.0, v110
	v_add_f32_e32 v106, 1.0, v106
	v_rcp_f32_e32 v116, v110
	v_rcp_f32_e32 v117, v106
	v_lshlrev_b32_e32 v110, 16, v111
	v_and_b32_e32 v111, 0xffff0000, v111
	v_mul_f32_e32 v64, 0xbfb8aa3b, v64
	v_pk_mul_f32 v[114:115], v[116:117], v[114:115]
	v_mul_f32_e32 v65, 0xbfb8aa3b, v65
	v_pk_mul_f32 v[102:103], v[102:103], v[114:115]
	v_lshlrev_b32_e32 v114, 16, v107
	v_cvt_pk_bf16_f32 v102, v102, v103
	v_mul_f32_e32 v103, 0xbfb8aa3b, v104
	v_exp_f32_e32 v103, v103
	v_and_b32_e32 v115, 0xffff0000, v107
	v_exp_f32_e32 v64, v64
	v_exp_f32_e32 v65, v65
	v_add_f32_e32 v103, 1.0, v103
	v_rcp_f32_e32 v104, v103
	v_mul_f32_e32 v103, 0xbfb8aa3b, v105
	v_exp_f32_e32 v103, v103
	v_add_f32_e32 v64, 1.0, v64
	v_add_f32_e32 v65, 1.0, v65
	v_rcp_f32_e32 v64, v64
	v_add_f32_e32 v103, 1.0, v103
	v_rcp_f32_e32 v105, v103
	v_mul_f32_e32 v103, 0xbfb8aa3b, v110
	v_exp_f32_e32 v103, v103
	v_rcp_f32_e32 v65, v65
	v_pk_mul_f32 v[104:105], v[104:105], v[114:115]
	v_mul_f32_e32 v56, 0xbfb8aa3b, v56
	v_add_f32_e32 v103, 1.0, v103
	v_rcp_f32_e32 v106, v103
	v_mul_f32_e32 v103, 0xbfb8aa3b, v111
	v_exp_f32_e32 v103, v103
	v_mul_f32_e32 v57, 0xbfb8aa3b, v57
	v_exp_f32_e32 v56, v56
	v_exp_f32_e32 v57, v57
	v_add_f32_e32 v103, 1.0, v103
	v_rcp_f32_e32 v107, v103
	v_add_f32_e32 v56, 1.0, v56
	v_add_f32_e32 v57, 1.0, v57
	v_rcp_f32_e32 v56, v56
	v_pk_mul_f32 v[106:107], v[106:107], v[110:111]
	v_lshlrev_b32_e32 v110, 16, v108
	v_pk_mul_f32 v[104:105], v[104:105], v[106:107]
	v_and_b32_e32 v111, 0xffff0000, v108
	v_cvt_pk_bf16_f32 v103, v104, v105
	v_lshlrev_b32_e32 v104, 16, v112
	v_and_b32_e32 v105, 0xffff0000, v112
	v_mul_f32_e32 v106, 0xbfb8aa3b, v104
	v_mul_f32_e32 v107, 0xbfb8aa3b, v105
	v_exp_f32_e32 v106, v106
	v_exp_f32_e32 v107, v107
	v_pk_mul_f32 v[98:99], v[98:99], v[110:111]
	v_lshlrev_b32_e32 v108, 16, v109
	v_add_f32_e32 v106, 1.0, v106
	v_add_f32_e32 v107, 1.0, v107
	v_rcp_f32_e32 v106, v106
	v_rcp_f32_e32 v107, v107
	v_and_b32_e32 v109, 0xffff0000, v109
	v_rcp_f32_e32 v57, v57
	v_mul_f32_e32 v52, 0xbfb8aa3b, v52
	v_pk_mul_f32 v[104:105], v[106:107], v[104:105]
	v_mul_f32_e32 v53, 0xbfb8aa3b, v53
	v_pk_mul_f32 v[98:99], v[98:99], v[104:105]
	v_exp_f32_e32 v52, v52
	v_cvt_pk_bf16_f32 v104, v98, v99
	v_mul_f32_e32 v98, 0xbfb8aa3b, v100
	v_lshlrev_b32_e32 v100, 16, v113
	v_mul_f32_e32 v105, 0xbfb8aa3b, v100
	v_exp_f32_e32 v105, v105
	v_mul_f32_e32 v99, 0xbfb8aa3b, v101
	v_and_b32_e32 v101, 0xffff0000, v113
	v_exp_f32_e32 v98, v98
	v_add_f32_e32 v105, 1.0, v105
	v_rcp_f32_e32 v106, v105
	v_mul_f32_e32 v105, 0xbfb8aa3b, v101
	v_exp_f32_e32 v99, v99
	v_exp_f32_e32 v105, v105
	v_add_f32_e32 v98, 1.0, v98
	v_rcp_f32_e32 v98, v98
	v_add_f32_e32 v99, 1.0, v99
	v_add_f32_e32 v105, 1.0, v105
; __device__ __forceinline__ float sigm(float v) { return __builtin_amdgcn_rcpf(1.0f + __builtin_amdgcn_exp2f(-LOG2E * v)); }
; __device__ __forceinline__ float bf_lo(unsigned w) { return __uint_as_float(w << 16); }
; __device__ __forceinline__ float silu_f(float v) { return v * __builtin_amdgcn_rcpf(1.0f + __builtin_amdgcn_exp2f(-1.4426950408889634f * v)); }
; __device__ __forceinline__ float bf_hi(unsigned w) { return __uint_as_float(w & 0xffff0000u); }
; __device__ __forceinline__ unsigned cvt_pk_bf16(float lo, float hi) { f32x2_t v = {lo, hi}; bf16x2_t b = __builtin_convertvector(v, bf16x2_t); return __builtin_bit_cast(unsigned, b); }
;     __device__ __forceinline__ void operator()(const f32x4 (&acc)[2][2][4][2], const Unit& u, int wr, int wc, int fr, int fq) const {
;     ...
;             for (int ai = 0; ai < 2; ++ai) {
;                 u32x4 ygv[4], sgv[4];
; #pragma unroll
;                 for (int m = 0; m < 4; ++m) { const unsigned rl = rl0 + (unsigned)(ai * HALF + m * 16);
;                     ygv[m] = *(const u32x4*)(ygb + (rl * 256u + col) * 2u); sgv[m] = *(const u32x4*)(sgb + (rl * 512u + col) * 2u); }
; #pragma unroll
;                 for (int m = 0; m < 4; ++m) { const unsigned rl = rl0 + (unsigned)(ai * HALF + m * 16);
;                     const u32x4 yg = ygv[m], sg = sgv[m];
;                     const f32x4 v0 = acc[ai][bj][m][0], v1 = acc[ai][bj][m][1];
;                     u32x4 w;
;                     w.x = cvt_pk_bf16(bf_lo(yg.x) * sigm(v0[0]) * silu_f(bf_lo(sg.x)), bf_hi(yg.x) * sigm(v0[1]) * silu_f(bf_hi(sg.x)));
;                     w.y = cvt_pk_bf16(bf_lo(yg.y) * sigm(v0[2]) * silu_f(bf_lo(sg.y)), bf_hi(yg.y) * sigm(v0[3]) * silu_f(bf_hi(sg.y)));
;                     w.z = cvt_pk_bf16(bf_lo(yg.z) * sigm(v1[0]) * silu_f(bf_lo(sg.z)), bf_hi(yg.z) * sigm(v1[1]) * silu_f(bf_hi(sg.z)));
;                     w.w = cvt_pk_bf16(bf_lo(yg.w) * sigm(v1[2]) * silu_f(bf_lo(sg.w)), bf_hi(yg.w) * sigm(v1[3]) * silu_f(bf_hi(sg.w)));
;                     *(u32x4*)(yb + (rl * 1024u + col) * 2u) = w; }
	v_rcp_f32_e32 v99, v99
	v_rcp_f32_e32 v107, v105
	v_exp_f32_e32 v53, v53
	v_add_f32_e32 v52, 1.0, v52
	v_pk_mul_f32 v[98:99], v[98:99], v[108:109]
	v_pk_mul_f32 v[100:101], v[106:107], v[100:101]
	v_add_f32_e32 v53, 1.0, v53
	v_pk_mul_f32 v[98:99], v[98:99], v[100:101]
	v_rcp_f32_e32 v52, v52
	v_cvt_pk_bf16_f32 v105, v98, v99
	v_add_u32_e32 v98, 0x18000, v146
	global_store_dwordx4 v98, v[102:105], s[60:61] offset:1536
	v_rcp_f32_e32 v53, v53
	v_lshlrev_b32_e32 v98, 9, v174
	v_add_u32_e32 v99, 0x10000, v98
	v_add_u32_e32 v100, v99, v176
	v_add_u32_e32 v99, v100, v99
	global_load_dwordx4 v[122:125], v100, s[62:63] nt
	global_load_dwordx4 v[126:129], v99, s[64:65] nt
	v_add_u32_e32 v99, 0x12000, v98
	v_add_u32_e32 v100, v99, v176
	v_add_u32_e32 v99, v100, v99
	global_load_dwordx4 v[114:117], v100, s[62:63] nt
	global_load_dwordx4 v[118:121], v99, s[64:65] nt
	v_add_u32_e32 v99, 0x14000, v98
	v_add_u32_e32 v102, 0x16000, v98
	v_add_u32_e32 v100, v99, v176
	v_add_u32_e32 v103, v102, v176
	v_add_u32_e32 v99, v100, v99
	v_add_u32_e32 v102, v103, v102
	global_load_dwordx4 v[106:109], v100, s[62:63] nt
	global_load_dwordx4 v[110:113], v99, s[64:65] nt
	v_mul_f32_e32 v48, 0xbfb8aa3b, v48
	global_load_dwordx4 v[98:101], v103, s[62:63] nt
	v_mul_f32_e32 v49, 0xbfb8aa3b, v49
	global_load_dwordx4 v[102:105], v102, s[64:65] nt
	v_exp_f32_e32 v48, v48
	v_exp_f32_e32 v49, v49
	v_mul_f32_e32 v44, 0xbfb8aa3b, v44
	v_mul_f32_e32 v45, 0xbfb8aa3b, v45
	v_add_f32_e32 v48, 1.0, v48
	v_add_f32_e32 v49, 1.0, v49
	v_rcp_f32_e32 v48, v48
	v_rcp_f32_e32 v49, v49
	v_exp_f32_e32 v44, v44
	v_exp_f32_e32 v45, v45
	v_mul_f32_e32 v40, 0xbfb8aa3b, v40
	v_mul_f32_e32 v41, 0xbfb8aa3b, v41
	v_add_f32_e32 v44, 1.0, v44
	v_add_f32_e32 v45, 1.0, v45
	v_rcp_f32_e32 v44, v44
	v_rcp_f32_e32 v45, v45
	v_exp_f32_e32 v40, v40
	v_exp_f32_e32 v41, v41
	v_mul_f32_e32 v36, 0xbfb8aa3b, v36
	v_mul_f32_e32 v37, 0xbfb8aa3b, v37
	v_add_f32_e32 v40, 1.0, v40
	v_add_f32_e32 v41, 1.0, v41
	v_rcp_f32_e32 v40, v40
	v_rcp_f32_e32 v41, v41
	v_exp_f32_e32 v36, v36
	v_exp_f32_e32 v37, v37
	v_mul_f32_e32 v32, 0xbfb8aa3b, v32
	v_mul_f32_e32 v33, 0xbfb8aa3b, v33
	v_add_f32_e32 v36, 1.0, v36
	v_add_f32_e32 v37, 1.0, v37
	v_rcp_f32_e32 v36, v36
	v_rcp_f32_e32 v37, v37
	v_exp_f32_e32 v32, v32
	v_exp_f32_e32 v33, v33
	v_mul_f32_e32 v28, 0xbfb8aa3b, v28
	v_mul_f32_e32 v29, 0xbfb8aa3b, v29
	v_add_f32_e32 v32, 1.0, v32
	v_add_f32_e32 v33, 1.0, v33
	v_rcp_f32_e32 v32, v32
	v_rcp_f32_e32 v33, v33
	v_exp_f32_e32 v28, v28
	v_exp_f32_e32 v29, v29
	v_mul_f32_e32 v24, 0xbfb8aa3b, v24
	v_mul_f32_e32 v25, 0xbfb8aa3b, v25
	v_add_f32_e32 v28, 1.0, v28
	v_add_f32_e32 v29, 1.0, v29
	v_rcp_f32_e32 v28, v28
	v_rcp_f32_e32 v29, v29
	v_exp_f32_e32 v24, v24
	v_exp_f32_e32 v25, v25
	v_mul_f32_e32 v20, 0xbfb8aa3b, v20
	v_mul_f32_e32 v21, 0xbfb8aa3b, v21
	v_add_f32_e32 v24, 1.0, v24
	v_add_f32_e32 v25, 1.0, v25
	v_rcp_f32_e32 v24, v24
	v_rcp_f32_e32 v25, v25
	v_exp_f32_e32 v20, v20
	v_exp_f32_e32 v21, v21
	v_mul_f32_e32 v16, 0xbfb8aa3b, v16
	v_mul_f32_e32 v17, 0xbfb8aa3b, v17
	v_add_f32_e32 v20, 1.0, v20
	s_waitcnt vmcnt(7)
	v_lshlrev_b32_e32 v134, 16, v122
	s_waitcnt vmcnt(6)
	v_lshlrev_b32_e32 v130, 16, v126
	v_and_b32_e32 v131, 0xffff0000, v126
	v_mul_f32_e32 v126, 0xbfb8aa3b, v130
	v_and_b32_e32 v135, 0xffff0000, v122
	v_mul_f32_e32 v122, 0xbfb8aa3b, v131
	v_exp_f32_e32 v126, v126
	v_exp_f32_e32 v122, v122
	v_pk_mul_f32 v[92:93], v[92:93], v[134:135]
	v_add_f32_e32 v21, 1.0, v21
	v_add_f32_e32 v126, 1.0, v126
	v_add_f32_e32 v122, 1.0, v122
	v_rcp_f32_e32 v132, v126
	v_rcp_f32_e32 v133, v122
	v_lshlrev_b32_e32 v126, 16, v127
	v_and_b32_e32 v127, 0xffff0000, v127
	v_rcp_f32_e32 v20, v20
	v_pk_mul_f32 v[130:131], v[132:133], v[130:131]
	v_rcp_f32_e32 v21, v21
	v_pk_mul_f32 v[92:93], v[92:93], v[130:131]
	v_lshlrev_b32_e32 v130, 16, v123
	v_cvt_pk_bf16_f32 v92, v92, v93
	v_mul_f32_e32 v93, 0xbfb8aa3b, v94
	v_exp_f32_e32 v93, v93
	v_and_b32_e32 v131, 0xffff0000, v123
	v_exp_f32_e32 v16, v16
	v_exp_f32_e32 v17, v17
	v_add_f32_e32 v93, 1.0, v93
	v_rcp_f32_e32 v94, v93
	v_mul_f32_e32 v93, 0xbfb8aa3b, v95
	v_exp_f32_e32 v93, v93
	v_add_f32_e32 v16, 1.0, v16
	v_add_f32_e32 v17, 1.0, v17
	v_rcp_f32_e32 v16, v16
	v_add_f32_e32 v93, 1.0, v93
	v_rcp_f32_e32 v95, v93
	v_mul_f32_e32 v93, 0xbfb8aa3b, v126
	v_exp_f32_e32 v93, v93
	v_rcp_f32_e32 v17, v17
	v_pk_mul_f32 v[94:95], v[94:95], v[130:131]
	v_mul_f32_e32 v12, 0xbfb8aa3b, v12
	v_add_f32_e32 v93, 1.0, v93
	v_rcp_f32_e32 v122, v93
	v_mul_f32_e32 v93, 0xbfb8aa3b, v127
	v_exp_f32_e32 v93, v93
	v_mul_f32_e32 v13, 0xbfb8aa3b, v13
	v_exp_f32_e32 v12, v12
	v_exp_f32_e32 v13, v13
	v_add_f32_e32 v93, 1.0, v93
	v_rcp_f32_e32 v123, v93
	v_add_f32_e32 v12, 1.0, v12
	v_add_f32_e32 v13, 1.0, v13
	v_rcp_f32_e32 v12, v12
	v_pk_mul_f32 v[122:123], v[122:123], v[126:127]
	v_lshlrev_b32_e32 v126, 16, v124
	v_pk_mul_f32 v[94:95], v[94:95], v[122:123]
	v_and_b32_e32 v127, 0xffff0000, v124
	v_cvt_pk_bf16_f32 v93, v94, v95
	v_lshlrev_b32_e32 v94, 16, v128
	v_and_b32_e32 v95, 0xffff0000, v128
	v_mul_f32_e32 v122, 0xbfb8aa3b, v94
	v_mul_f32_e32 v123, 0xbfb8aa3b, v95
	v_exp_f32_e32 v122, v122
	v_exp_f32_e32 v123, v123
	v_pk_mul_f32 v[88:89], v[88:89], v[126:127]
	v_lshlrev_b32_e32 v124, 16, v125
	v_add_f32_e32 v122, 1.0, v122
	v_add_f32_e32 v123, 1.0, v123
	v_rcp_f32_e32 v122, v122
	v_rcp_f32_e32 v123, v123
	v_and_b32_e32 v125, 0xffff0000, v125
	v_rcp_f32_e32 v13, v13
	v_mul_f32_e32 v8, 0xbfb8aa3b, v8
	v_pk_mul_f32 v[94:95], v[122:123], v[94:95]
	v_mul_f32_e32 v9, 0xbfb8aa3b, v9
	v_pk_mul_f32 v[88:89], v[88:89], v[94:95]
	v_exp_f32_e32 v8, v8
	v_cvt_pk_bf16_f32 v94, v88, v89
	v_mul_f32_e32 v88, 0xbfb8aa3b, v90
	v_lshlrev_b32_e32 v90, 16, v129
	v_mul_f32_e32 v95, 0xbfb8aa3b, v90
	v_exp_f32_e32 v95, v95
	v_mul_f32_e32 v89, 0xbfb8aa3b, v91
	v_and_b32_e32 v91, 0xffff0000, v129
	v_exp_f32_e32 v88, v88
	v_add_f32_e32 v95, 1.0, v95
	v_rcp_f32_e32 v122, v95
	v_mul_f32_e32 v95, 0xbfb8aa3b, v91
	v_exp_f32_e32 v89, v89
	v_exp_f32_e32 v95, v95
	v_add_f32_e32 v88, 1.0, v88
	v_rcp_f32_e32 v88, v88
	v_add_f32_e32 v89, 1.0, v89
	v_add_f32_e32 v95, 1.0, v95
	v_rcp_f32_e32 v89, v89
	v_rcp_f32_e32 v123, v95
	v_exp_f32_e32 v9, v9
	v_add_f32_e32 v8, 1.0, v8
	v_pk_mul_f32 v[88:89], v[88:89], v[124:125]
	v_pk_mul_f32 v[90:91], v[122:123], v[90:91]
	v_add_f32_e32 v9, 1.0, v9
	v_pk_mul_f32 v[88:89], v[88:89], v[90:91]
	s_waitcnt vmcnt(4)
; __device__ __forceinline__ float sigm(float v) { return __builtin_amdgcn_rcpf(1.0f + __builtin_amdgcn_exp2f(-LOG2E * v)); }
; __device__ __forceinline__ float bf_lo(unsigned w) { return __uint_as_float(w << 16); }
; __device__ __forceinline__ float silu_f(float v) { return v * __builtin_amdgcn_rcpf(1.0f + __builtin_amdgcn_exp2f(-1.4426950408889634f * v)); }
; __device__ __forceinline__ float bf_hi(unsigned w) { return __uint_as_float(w & 0xffff0000u); }
; __device__ __forceinline__ unsigned cvt_pk_bf16(float lo, float hi) { f32x2_t v = {lo, hi}; bf16x2_t b = __builtin_convertvector(v, bf16x2_t); return __builtin_bit_cast(unsigned, b); }
;     __device__ __forceinline__ void operator()(const f32x4 (&acc)[2][2][4][2], const Unit& u, int wr, int wc, int fr, int fq) const {
;     ...
;                 for (int m = 0; m < 4; ++m) { const unsigned rl = rl0 + (unsigned)(ai * HALF + m * 16);
;                     const u32x4 yg = ygv[m], sg = sgv[m];
;                     const f32x4 v0 = acc[ai][bj][m][0], v1 = acc[ai][bj][m][1];
;                     u32x4 w;
;                     w.x = cvt_pk_bf16(bf_lo(yg.x) * sigm(v0[0]) * silu_f(bf_lo(sg.x)), bf_hi(yg.x) * sigm(v0[1]) * silu_f(bf_hi(sg.x)));
;                     w.y = cvt_pk_bf16(bf_lo(yg.y) * sigm(v0[2]) * silu_f(bf_lo(sg.y)), bf_hi(yg.y) * sigm(v0[3]) * silu_f(bf_hi(sg.y)));
;                     w.z = cvt_pk_bf16(bf_lo(yg.z) * sigm(v1[0]) * silu_f(bf_lo(sg.z)), bf_hi(yg.z) * sigm(v1[1]) * silu_f(bf_hi(sg.z)));
;                     w.w = cvt_pk_bf16(bf_lo(yg.w) * sigm(v1[2]) * silu_f(bf_lo(sg.w)), bf_hi(yg.w) * sigm(v1[3]) * silu_f(bf_hi(sg.w)));
;                     *(u32x4*)(yb + (rl * 1024u + col) * 2u) = w; }
	v_lshlrev_b32_e32 v90, 16, v118
	v_cvt_pk_bf16_f32 v95, v88, v89
	v_lshl_add_u32 v88, v174, 11, v176
	v_add_u32_e32 v89, 0x40000, v88
	global_store_dwordx4 v89, v[92:95], s[60:61] offset:1536
	v_mul_f32_e32 v89, 0xbfb8aa3b, v90
	v_exp_f32_e32 v89, v89
	v_and_b32_e32 v91, 0xffff0000, v118
	v_lshlrev_b32_e32 v94, 16, v114
	v_and_b32_e32 v95, 0xffff0000, v114
	v_add_f32_e32 v89, 1.0, v89
	v_rcp_f32_e32 v92, v89
	v_mul_f32_e32 v89, 0xbfb8aa3b, v91
	v_exp_f32_e32 v89, v89
	v_pk_mul_f32 v[84:85], v[84:85], v[94:95]
	v_lshlrev_b32_e32 v94, 16, v115
	v_and_b32_e32 v95, 0xffff0000, v115
	v_add_f32_e32 v89, 1.0, v89
	v_rcp_f32_e32 v93, v89
	v_rcp_f32_e32 v8, v8
	v_rcp_f32_e32 v9, v9
	v_mul_f32_e32 v4, 0xbfb8aa3b, v4
	v_pk_mul_f32 v[90:91], v[92:93], v[90:91]
	v_mul_f32_e32 v5, 0xbfb8aa3b, v5
	v_pk_mul_f32 v[84:85], v[84:85], v[90:91]
	v_lshlrev_b32_e32 v90, 16, v119
	v_cvt_pk_bf16_f32 v84, v84, v85
	v_mul_f32_e32 v85, 0xbfb8aa3b, v86
	v_exp_f32_e32 v85, v85
	v_and_b32_e32 v91, 0xffff0000, v119
	v_exp_f32_e32 v4, v4
	v_exp_f32_e32 v5, v5
	v_add_f32_e32 v85, 1.0, v85
	v_rcp_f32_e32 v86, v85
	v_mul_f32_e32 v85, 0xbfb8aa3b, v87
	v_exp_f32_e32 v85, v85
	v_add_f32_e32 v4, 1.0, v4
	v_add_f32_e32 v5, 1.0, v5
	v_rcp_f32_e32 v4, v4
	v_add_f32_e32 v85, 1.0, v85
	v_rcp_f32_e32 v87, v85
	v_mul_f32_e32 v85, 0xbfb8aa3b, v90
	v_exp_f32_e32 v85, v85
	v_rcp_f32_e32 v5, v5
	v_pk_mul_f32 v[86:87], v[86:87], v[94:95]
	v_mul_f32_e32 v0, 0xbfb8aa3b, v0
	v_add_f32_e32 v85, 1.0, v85
	v_rcp_f32_e32 v92, v85
	v_mul_f32_e32 v85, 0xbfb8aa3b, v91
	v_exp_f32_e32 v85, v85
	v_mul_f32_e32 v1, 0xbfb8aa3b, v1
	v_exp_f32_e32 v0, v0
	v_exp_f32_e32 v1, v1
	v_add_f32_e32 v85, 1.0, v85
	v_rcp_f32_e32 v93, v85
	v_add_f32_e32 v0, 1.0, v0
	v_add_f32_e32 v1, 1.0, v1
	v_rcp_f32_e32 v0, v0
	v_pk_mul_f32 v[90:91], v[92:93], v[90:91]
	v_lshlrev_b32_e32 v92, 16, v116
	v_pk_mul_f32 v[86:87], v[86:87], v[90:91]
	v_and_b32_e32 v93, 0xffff0000, v116
	v_cvt_pk_bf16_f32 v85, v86, v87
	v_lshlrev_b32_e32 v86, 16, v120
	v_mul_f32_e32 v89, 0xbfb8aa3b, v86
	v_exp_f32_e32 v89, v89
	v_and_b32_e32 v87, 0xffff0000, v120
	v_pk_mul_f32 v[80:81], v[80:81], v[92:93]
	v_lshlrev_b32_e32 v92, 16, v117
	v_add_f32_e32 v89, 1.0, v89
	v_rcp_f32_e32 v90, v89
	v_mul_f32_e32 v89, 0xbfb8aa3b, v87
	v_exp_f32_e32 v89, v89
	v_and_b32_e32 v93, 0xffff0000, v117
	v_rcp_f32_e32 v1, v1
	s_and_b64 vcc, exec, s[38:39]
	v_add_f32_e32 v89, 1.0, v89
	v_rcp_f32_e32 v91, v89
	s_nop 0
	v_pk_mul_f32 v[86:87], v[90:91], v[86:87]
	s_nop 0
	v_pk_mul_f32 v[80:81], v[80:81], v[86:87]
	s_nop 0
	v_cvt_pk_bf16_f32 v86, v80, v81
	v_mul_f32_e32 v80, 0xbfb8aa3b, v82
	v_lshlrev_b32_e32 v82, 16, v121
	v_mul_f32_e32 v87, 0xbfb8aa3b, v82
	v_exp_f32_e32 v87, v87
	v_mul_f32_e32 v81, 0xbfb8aa3b, v83
	v_and_b32_e32 v83, 0xffff0000, v121
	v_exp_f32_e32 v80, v80
	v_add_f32_e32 v87, 1.0, v87
	v_rcp_f32_e32 v90, v87
	v_mul_f32_e32 v87, 0xbfb8aa3b, v83
	v_exp_f32_e32 v81, v81
	v_exp_f32_e32 v87, v87
	v_add_f32_e32 v80, 1.0, v80
	v_rcp_f32_e32 v80, v80
	v_add_f32_e32 v81, 1.0, v81
	v_add_f32_e32 v87, 1.0, v87
	v_rcp_f32_e32 v81, v81
	v_rcp_f32_e32 v91, v87
	v_pk_mul_f32 v[80:81], v[80:81], v[92:93]
	v_pk_mul_f32 v[82:83], v[90:91], v[82:83]
	s_nop 0
	v_pk_mul_f32 v[80:81], v[80:81], v[82:83]
	s_nop 0
	v_cvt_pk_bf16_f32 v87, v80, v81
	v_add_u32_e32 v80, 0x48000, v88
	global_store_dwordx4 v80, v[84:87], s[60:61] offset:1536
	s_waitcnt vmcnt(4)
	v_lshlrev_b32_e32 v80, 16, v110
	v_and_b32_e32 v81, 0xffff0000, v110
	v_mul_f32_e32 v82, 0xbfb8aa3b, v80
	v_mul_f32_e32 v83, 0xbfb8aa3b, v81
	v_exp_f32_e32 v82, v82
	v_exp_f32_e32 v83, v83
	v_lshlrev_b32_e32 v84, 16, v106
	v_and_b32_e32 v85, 0xffff0000, v106
	v_add_f32_e32 v82, 1.0, v82
	v_add_f32_e32 v83, 1.0, v83
	v_rcp_f32_e32 v82, v82
	v_rcp_f32_e32 v83, v83
	v_pk_mul_f32 v[76:77], v[76:77], v[84:85]
	v_lshlrev_b32_e32 v84, 16, v107
	v_and_b32_e32 v85, 0xffff0000, v107
	v_pk_mul_f32 v[80:81], v[82:83], v[80:81]
	s_nop 0
	v_pk_mul_f32 v[76:77], v[76:77], v[80:81]
	v_lshlrev_b32_e32 v80, 16, v111
	v_cvt_pk_bf16_f32 v76, v76, v77
	v_mul_f32_e32 v77, 0xbfb8aa3b, v78
	v_exp_f32_e32 v77, v77
	v_and_b32_e32 v81, 0xffff0000, v111
	v_add_f32_e32 v77, 1.0, v77
	v_rcp_f32_e32 v78, v77
	v_mul_f32_e32 v77, 0xbfb8aa3b, v79
	v_exp_f32_e32 v77, v77
	s_nop 0
	v_add_f32_e32 v77, 1.0, v77
	v_rcp_f32_e32 v79, v77
	v_mul_f32_e32 v77, 0xbfb8aa3b, v80
	v_exp_f32_e32 v77, v77
	v_pk_mul_f32 v[78:79], v[78:79], v[84:85]
	v_add_f32_e32 v77, 1.0, v77
	v_rcp_f32_e32 v82, v77
	v_mul_f32_e32 v77, 0xbfb8aa3b, v81
	v_exp_f32_e32 v77, v77
	s_nop 0
	v_add_f32_e32 v77, 1.0, v77
	v_rcp_f32_e32 v83, v77
	s_nop 0
	v_pk_mul_f32 v[80:81], v[82:83], v[80:81]
	s_nop 0
	v_pk_mul_f32 v[78:79], v[78:79], v[80:81]
	v_lshlrev_b32_e32 v82, 16, v108
	v_cvt_pk_bf16_f32 v77, v78, v79
	v_lshlrev_b32_e32 v78, 16, v112
	v_and_b32_e32 v79, 0xffff0000, v112
	v_mul_f32_e32 v80, 0xbfb8aa3b, v78
	v_mul_f32_e32 v81, 0xbfb8aa3b, v79
	v_exp_f32_e32 v80, v80
	v_exp_f32_e32 v81, v81
	v_and_b32_e32 v83, 0xffff0000, v108
	v_pk_mul_f32 v[72:73], v[72:73], v[82:83]
	v_add_f32_e32 v80, 1.0, v80
	v_add_f32_e32 v81, 1.0, v81
	v_rcp_f32_e32 v80, v80
	v_rcp_f32_e32 v81, v81
	v_lshlrev_b32_e32 v82, 16, v109
	v_and_b32_e32 v83, 0xffff0000, v109
	v_pk_mul_f32 v[78:79], v[80:81], v[78:79]
	s_nop 0
	v_pk_mul_f32 v[72:73], v[72:73], v[78:79]
	s_nop 0
	v_cvt_pk_bf16_f32 v78, v72, v73
	v_mul_f32_e32 v72, 0xbfb8aa3b, v74
	v_lshlrev_b32_e32 v74, 16, v113
	v_mul_f32_e32 v79, 0xbfb8aa3b, v74
	v_exp_f32_e32 v79, v79
	v_mul_f32_e32 v73, 0xbfb8aa3b, v75
	v_and_b32_e32 v75, 0xffff0000, v113
	v_exp_f32_e32 v72, v72
	v_add_f32_e32 v79, 1.0, v79
	v_rcp_f32_e32 v80, v79
	v_mul_f32_e32 v79, 0xbfb8aa3b, v75
	v_exp_f32_e32 v73, v73
	v_exp_f32_e32 v79, v79
	v_add_f32_e32 v72, 1.0, v72
	v_rcp_f32_e32 v72, v72
	v_add_f32_e32 v73, 1.0, v73
	v_add_f32_e32 v79, 1.0, v79
	v_rcp_f32_e32 v73, v73
	v_rcp_f32_e32 v81, v79
	v_pk_mul_f32 v[72:73], v[72:73], v[82:83]
	v_pk_mul_f32 v[74:75], v[80:81], v[74:75]
	s_nop 0
	v_pk_mul_f32 v[72:73], v[72:73], v[74:75]
	s_nop 0
	v_cvt_pk_bf16_f32 v79, v72, v73
	v_add_u32_e32 v72, 0x50000, v88
	global_store_dwordx4 v72, v[76:79], s[60:61] offset:1536
	s_waitcnt vmcnt(3)
; __device__ __forceinline__ float sigm(float v) { return __builtin_amdgcn_rcpf(1.0f + __builtin_amdgcn_exp2f(-LOG2E * v)); }
; __device__ __forceinline__ float bf_lo(unsigned w) { return __uint_as_float(w << 16); }
; __device__ __forceinline__ float silu_f(float v) { return v * __builtin_amdgcn_rcpf(1.0f + __builtin_amdgcn_exp2f(-1.4426950408889634f * v)); }
; __device__ __forceinline__ float bf_hi(unsigned w) { return __uint_as_float(w & 0xffff0000u); }
; __device__ __forceinline__ unsigned cvt_pk_bf16(float lo, float hi) { f32x2_t v = {lo, hi}; bf16x2_t b = __builtin_convertvector(v, bf16x2_t); return __builtin_bit_cast(unsigned, b); }
;     __device__ __forceinline__ void operator()(const f32x4 (&acc)[2][2][4][2], const Unit& u, int wr, int wc, int fr, int fq) const {
;     ...
;                 for (int m = 0; m < 4; ++m) { const unsigned rl = rl0 + (unsigned)(ai * HALF + m * 16);
;                     ygv[m] = *(const u32x4*)(ygb + (rl * 256u + col) * 2u); sgv[m] = *(const u32x4*)(sgb + (rl * 512u + col) * 2u); }
; #pragma unroll
;                 for (int m = 0; m < 4; ++m) { const unsigned rl = rl0 + (unsigned)(ai * HALF + m * 16);
;                     const u32x4 yg = ygv[m], sg = sgv[m];
;                     const f32x4 v0 = acc[ai][bj][m][0], v1 = acc[ai][bj][m][1];
;                     u32x4 w;
;                     w.x = cvt_pk_bf16(bf_lo(yg.x) * sigm(v0[0]) * silu_f(bf_lo(sg.x)), bf_hi(yg.x) * sigm(v0[1]) * silu_f(bf_hi(sg.x)));
;                     w.y = cvt_pk_bf16(bf_lo(yg.y) * sigm(v0[2]) * silu_f(bf_lo(sg.y)), bf_hi(yg.y) * sigm(v0[3]) * silu_f(bf_hi(sg.y)));
;                     w.z = cvt_pk_bf16(bf_lo(yg.z) * sigm(v1[0]) * silu_f(bf_lo(sg.z)), bf_hi(yg.z) * sigm(v1[1]) * silu_f(bf_hi(sg.z)));
;                     w.w = cvt_pk_bf16(bf_lo(yg.w) * sigm(v1[2]) * silu_f(bf_lo(sg.w)), bf_hi(yg.w) * sigm(v1[3]) * silu_f(bf_hi(sg.w)));
;                     *(u32x4*)(yb + (rl * 1024u + col) * 2u) = w; }
	v_lshlrev_b32_e32 v72, 16, v102
	v_and_b32_e32 v73, 0xffff0000, v102
	v_mul_f32_e32 v74, 0xbfb8aa3b, v72
	v_mul_f32_e32 v75, 0xbfb8aa3b, v73
	v_exp_f32_e32 v74, v74
	v_exp_f32_e32 v75, v75
	v_lshlrev_b32_e32 v76, 16, v98
	v_and_b32_e32 v77, 0xffff0000, v98
	v_add_f32_e32 v74, 1.0, v74
	v_add_f32_e32 v75, 1.0, v75
	v_rcp_f32_e32 v74, v74
	v_rcp_f32_e32 v75, v75
	v_pk_mul_f32 v[68:69], v[68:69], v[76:77]
	v_lshlrev_b32_e32 v76, 16, v99
	v_and_b32_e32 v77, 0xffff0000, v99
	v_pk_mul_f32 v[72:73], v[74:75], v[72:73]
	s_nop 0
	v_pk_mul_f32 v[68:69], v[68:69], v[72:73]
	v_lshlrev_b32_e32 v72, 16, v103
	v_cvt_pk_bf16_f32 v68, v68, v69
	v_mul_f32_e32 v69, 0xbfb8aa3b, v70
	v_exp_f32_e32 v69, v69
	v_and_b32_e32 v73, 0xffff0000, v103
	v_add_f32_e32 v69, 1.0, v69
	v_rcp_f32_e32 v70, v69
	v_mul_f32_e32 v69, 0xbfb8aa3b, v71
	v_exp_f32_e32 v69, v69
	s_nop 0
	v_add_f32_e32 v69, 1.0, v69
	v_rcp_f32_e32 v71, v69
	v_mul_f32_e32 v69, 0xbfb8aa3b, v72
	v_exp_f32_e32 v69, v69
	v_pk_mul_f32 v[70:71], v[70:71], v[76:77]
	v_add_f32_e32 v69, 1.0, v69
	v_rcp_f32_e32 v74, v69
	v_mul_f32_e32 v69, 0xbfb8aa3b, v73
	v_exp_f32_e32 v69, v69
	s_nop 0
	v_add_f32_e32 v69, 1.0, v69
	v_rcp_f32_e32 v75, v69
	s_nop 0
	v_pk_mul_f32 v[72:73], v[74:75], v[72:73]
	s_nop 0
	v_pk_mul_f32 v[70:71], v[70:71], v[72:73]
	v_lshlrev_b32_e32 v74, 16, v100
	v_cvt_pk_bf16_f32 v69, v70, v71
	v_lshlrev_b32_e32 v70, 16, v104
	v_and_b32_e32 v71, 0xffff0000, v104
	v_mul_f32_e32 v72, 0xbfb8aa3b, v70
	v_mul_f32_e32 v73, 0xbfb8aa3b, v71
	v_exp_f32_e32 v72, v72
	v_exp_f32_e32 v73, v73
	v_and_b32_e32 v75, 0xffff0000, v100
	v_pk_mul_f32 v[60:61], v[60:61], v[74:75]
	v_add_f32_e32 v72, 1.0, v72
	v_add_f32_e32 v73, 1.0, v73
	v_rcp_f32_e32 v72, v72
	v_rcp_f32_e32 v73, v73
	v_lshlrev_b32_e32 v74, 16, v101
	v_and_b32_e32 v75, 0xffff0000, v101
	v_pk_mul_f32 v[70:71], v[72:73], v[70:71]
	s_nop 0
	v_pk_mul_f32 v[60:61], v[60:61], v[70:71]
	s_nop 0
	v_cvt_pk_bf16_f32 v70, v60, v61
	v_mul_f32_e32 v60, 0xbfb8aa3b, v62
	v_lshlrev_b32_e32 v62, 16, v105
	v_mul_f32_e32 v71, 0xbfb8aa3b, v62
	v_exp_f32_e32 v71, v71
	v_mul_f32_e32 v61, 0xbfb8aa3b, v63
	v_and_b32_e32 v63, 0xffff0000, v105
	v_exp_f32_e32 v60, v60
	v_add_f32_e32 v71, 1.0, v71
	v_rcp_f32_e32 v72, v71
	v_mul_f32_e32 v71, 0xbfb8aa3b, v63
	v_exp_f32_e32 v61, v61
	v_exp_f32_e32 v71, v71
	v_add_f32_e32 v60, 1.0, v60
	v_rcp_f32_e32 v60, v60
	v_add_f32_e32 v61, 1.0, v61
	v_add_f32_e32 v71, 1.0, v71
	v_rcp_f32_e32 v61, v61
	v_rcp_f32_e32 v73, v71
	v_pk_mul_f32 v[60:61], v[60:61], v[74:75]
	v_pk_mul_f32 v[62:63], v[72:73], v[62:63]
	s_nop 0
	v_pk_mul_f32 v[60:61], v[60:61], v[62:63]
	s_nop 0
	v_cvt_pk_bf16_f32 v71, v60, v61
	v_add_u32_e32 v60, 0x58000, v88
	global_store_dwordx4 v60, v[68:71], s[60:61] offset:1536
	v_mov_b32_e32 v60, 0x100
	s_nop 0
	v_lshl_add_u32 v98, v175, 1, v60
	v_lshlrev_b32_e32 v60, 9, v174
	v_add_u32_e32 v61, v98, v60
	v_add_u32_e32 v99, v61, v60
	global_load_dwordx4 v[88:91], v61, s[62:63] nt
	global_load_dwordx4 v[92:95], v99, s[64:65] nt
	v_add_u32_e32 v61, 0x2000, v60
	v_add_u32_e32 v62, v61, v98
	v_add_u32_e32 v61, v62, v61
	global_load_dwordx4 v[80:83], v62, s[62:63] nt
	global_load_dwordx4 v[84:87], v61, s[64:65] nt
	v_add_u32_e32 v61, 0x4000, v60
	v_add_u32_e32 v68, 0x6000, v60
	v_add_u32_e32 v62, v61, v98
	v_add_u32_e32 v69, v68, v98
	v_add_u32_e32 v61, v62, v61
	v_add_u32_e32 v68, v69, v68
	global_load_dwordx4 v[72:75], v62, s[62:63] nt
	global_load_dwordx4 v[76:79], v61, s[64:65] nt
	s_waitcnt vmcnt(5)
	v_lshlrev_b32_e32 v104, 16, v88
	s_waitcnt vmcnt(4)
	v_lshlrev_b32_e32 v100, 16, v92
	v_and_b32_e32 v101, 0xffff0000, v92
	v_mul_f32_e32 v92, 0xbfb8aa3b, v100
	v_and_b32_e32 v105, 0xffff0000, v88
	v_mul_f32_e32 v88, 0xbfb8aa3b, v101
	v_exp_f32_e32 v92, v92
	v_exp_f32_e32 v88, v88
	v_pk_mul_f32 v[64:65], v[64:65], v[104:105]
	global_load_dwordx4 v[60:63], v69, s[62:63] nt
	v_add_f32_e32 v92, 1.0, v92
	v_add_f32_e32 v88, 1.0, v88
	v_rcp_f32_e32 v102, v92
	v_rcp_f32_e32 v103, v88
	v_lshlrev_b32_e32 v92, 16, v93
	v_and_b32_e32 v93, 0xffff0000, v93
	global_load_dwordx4 v[68:71], v68, s[64:65] nt
	v_pk_mul_f32 v[100:101], v[102:103], v[100:101]
	s_nop 0
	v_pk_mul_f32 v[64:65], v[64:65], v[100:101]
	v_lshlrev_b32_e32 v100, 16, v89
	v_cvt_pk_bf16_f32 v64, v64, v65
	v_mul_f32_e32 v65, 0xbfb8aa3b, v66
	v_exp_f32_e32 v65, v65
	v_and_b32_e32 v101, 0xffff0000, v89
	v_add_f32_e32 v65, 1.0, v65
	v_rcp_f32_e32 v66, v65
	v_mul_f32_e32 v65, 0xbfb8aa3b, v67
	v_exp_f32_e32 v65, v65
	s_nop 0
	v_add_f32_e32 v65, 1.0, v65
	v_rcp_f32_e32 v67, v65
	v_mul_f32_e32 v65, 0xbfb8aa3b, v92
	v_exp_f32_e32 v65, v65
	v_pk_mul_f32 v[66:67], v[66:67], v[100:101]
	v_add_f32_e32 v65, 1.0, v65
	v_rcp_f32_e32 v88, v65
	v_mul_f32_e32 v65, 0xbfb8aa3b, v93
	v_exp_f32_e32 v65, v65
	s_nop 0
	v_add_f32_e32 v65, 1.0, v65
	v_rcp_f32_e32 v89, v65
	s_nop 0
	v_pk_mul_f32 v[88:89], v[88:89], v[92:93]
	s_nop 0
	v_pk_mul_f32 v[66:67], v[66:67], v[88:89]
	v_lshlrev_b32_e32 v92, 16, v90
	v_cvt_pk_bf16_f32 v65, v66, v67
	v_lshlrev_b32_e32 v66, 16, v94
	v_and_b32_e32 v67, 0xffff0000, v94
	v_mul_f32_e32 v88, 0xbfb8aa3b, v66
	v_mul_f32_e32 v89, 0xbfb8aa3b, v67
	v_exp_f32_e32 v88, v88
	v_exp_f32_e32 v89, v89
	v_and_b32_e32 v93, 0xffff0000, v90
	v_pk_mul_f32 v[56:57], v[56:57], v[92:93]
	v_add_f32_e32 v88, 1.0, v88
	v_add_f32_e32 v89, 1.0, v89
	v_rcp_f32_e32 v88, v88
	v_rcp_f32_e32 v89, v89
	v_lshlrev_b32_e32 v90, 16, v91
	v_and_b32_e32 v91, 0xffff0000, v91
	v_pk_mul_f32 v[66:67], v[88:89], v[66:67]
	s_nop 0
	v_pk_mul_f32 v[56:57], v[56:57], v[66:67]
	s_nop 0
	v_cvt_pk_bf16_f32 v66, v56, v57
	v_mul_f32_e32 v56, 0xbfb8aa3b, v58
	v_lshlrev_b32_e32 v58, 16, v95
	v_mul_f32_e32 v67, 0xbfb8aa3b, v58
	v_exp_f32_e32 v67, v67
	v_mul_f32_e32 v57, 0xbfb8aa3b, v59
	v_and_b32_e32 v59, 0xffff0000, v95
	v_exp_f32_e32 v56, v56
	v_add_f32_e32 v67, 1.0, v67
	v_rcp_f32_e32 v88, v67
	v_mul_f32_e32 v67, 0xbfb8aa3b, v59
	v_exp_f32_e32 v57, v57
	v_exp_f32_e32 v67, v67
	v_add_f32_e32 v56, 1.0, v56
	v_rcp_f32_e32 v56, v56
	v_add_f32_e32 v57, 1.0, v57
	v_add_f32_e32 v67, 1.0, v67
	v_rcp_f32_e32 v57, v57
	v_rcp_f32_e32 v89, v67
	v_pk_mul_f32 v[56:57], v[56:57], v[90:91]
	v_pk_mul_f32 v[58:59], v[88:89], v[58:59]
	s_nop 0
	v_pk_mul_f32 v[56:57], v[56:57], v[58:59]
	s_waitcnt vmcnt(4)
; __device__ __forceinline__ float sigm(float v) { return __builtin_amdgcn_rcpf(1.0f + __builtin_amdgcn_exp2f(-LOG2E * v)); }
; __device__ __forceinline__ float bf_lo(unsigned w) { return __uint_as_float(w << 16); }
; __device__ __forceinline__ float silu_f(float v) { return v * __builtin_amdgcn_rcpf(1.0f + __builtin_amdgcn_exp2f(-1.4426950408889634f * v)); }
; __device__ __forceinline__ float bf_hi(unsigned w) { return __uint_as_float(w & 0xffff0000u); }
; __device__ __forceinline__ unsigned cvt_pk_bf16(float lo, float hi) { f32x2_t v = {lo, hi}; bf16x2_t b = __builtin_convertvector(v, bf16x2_t); return __builtin_bit_cast(unsigned, b); }
;     __device__ __forceinline__ void operator()(const f32x4 (&acc)[2][2][4][2], const Unit& u, int wr, int wc, int fr, int fq) const {
;     ...
;                 for (int m = 0; m < 4; ++m) { const unsigned rl = rl0 + (unsigned)(ai * HALF + m * 16);
;                     const u32x4 yg = ygv[m], sg = sgv[m];
;                     const f32x4 v0 = acc[ai][bj][m][0], v1 = acc[ai][bj][m][1];
;                     u32x4 w;
;                     w.x = cvt_pk_bf16(bf_lo(yg.x) * sigm(v0[0]) * silu_f(bf_lo(sg.x)), bf_hi(yg.x) * sigm(v0[1]) * silu_f(bf_hi(sg.x)));
;                     w.y = cvt_pk_bf16(bf_lo(yg.y) * sigm(v0[2]) * silu_f(bf_lo(sg.y)), bf_hi(yg.y) * sigm(v0[3]) * silu_f(bf_hi(sg.y)));
;                     w.z = cvt_pk_bf16(bf_lo(yg.z) * sigm(v1[0]) * silu_f(bf_lo(sg.z)), bf_hi(yg.z) * sigm(v1[1]) * silu_f(bf_hi(sg.z)));
;                     w.w = cvt_pk_bf16(bf_lo(yg.w) * sigm(v1[2]) * silu_f(bf_lo(sg.w)), bf_hi(yg.w) * sigm(v1[3]) * silu_f(bf_hi(sg.w)));
;                     *(u32x4*)(yb + (rl * 1024u + col) * 2u) = w; }
	v_lshlrev_b32_e32 v58, 16, v84
	v_cvt_pk_bf16_f32 v67, v56, v57
	v_mul_f32_e32 v57, 0xbfb8aa3b, v58
	v_exp_f32_e32 v57, v57
	v_lshl_add_u32 v56, v174, 10, v99
	v_and_b32_e32 v59, 0xffff0000, v84
	global_store_dwordx4 v56, v[64:67], s[60:61] offset:1536
	v_add_f32_e32 v57, 1.0, v57
	s_nop 0
	v_rcp_f32_e32 v64, v57
	v_mul_f32_e32 v57, 0xbfb8aa3b, v59
	v_exp_f32_e32 v57, v57
	v_lshlrev_b32_e32 v66, 16, v80
	v_and_b32_e32 v67, 0xffff0000, v80
	v_pk_mul_f32 v[52:53], v[52:53], v[66:67]
	v_add_f32_e32 v57, 1.0, v57
	v_rcp_f32_e32 v65, v57
	v_lshlrev_b32_e32 v66, 16, v81
	v_and_b32_e32 v67, 0xffff0000, v81
	v_pk_mul_f32 v[58:59], v[64:65], v[58:59]
	s_nop 0
	v_pk_mul_f32 v[52:53], v[52:53], v[58:59]
	v_lshlrev_b32_e32 v58, 16, v85
	v_cvt_pk_bf16_f32 v52, v52, v53
	v_mul_f32_e32 v53, 0xbfb8aa3b, v54
	v_exp_f32_e32 v53, v53
	v_and_b32_e32 v59, 0xffff0000, v85
	v_add_f32_e32 v53, 1.0, v53
	v_rcp_f32_e32 v54, v53
	v_mul_f32_e32 v53, 0xbfb8aa3b, v55
	v_exp_f32_e32 v53, v53
	s_nop 0
	v_add_f32_e32 v53, 1.0, v53
	v_rcp_f32_e32 v55, v53
	v_mul_f32_e32 v53, 0xbfb8aa3b, v58
	v_exp_f32_e32 v53, v53
	v_pk_mul_f32 v[54:55], v[54:55], v[66:67]
	v_add_f32_e32 v53, 1.0, v53
	v_rcp_f32_e32 v64, v53
	v_mul_f32_e32 v53, 0xbfb8aa3b, v59
	v_exp_f32_e32 v53, v53
	s_nop 0
	v_add_f32_e32 v53, 1.0, v53
	v_rcp_f32_e32 v65, v53
	s_nop 0
	v_pk_mul_f32 v[58:59], v[64:65], v[58:59]
	s_nop 0
	v_pk_mul_f32 v[54:55], v[54:55], v[58:59]
	v_lshlrev_b32_e32 v64, 16, v82
	v_cvt_pk_bf16_f32 v53, v54, v55
	v_lshlrev_b32_e32 v54, 16, v86
	v_mul_f32_e32 v57, 0xbfb8aa3b, v54
	v_exp_f32_e32 v57, v57
	v_and_b32_e32 v55, 0xffff0000, v86
	v_and_b32_e32 v65, 0xffff0000, v82
	v_pk_mul_f32 v[48:49], v[48:49], v[64:65]
	v_add_f32_e32 v57, 1.0, v57
	v_rcp_f32_e32 v58, v57
	v_mul_f32_e32 v57, 0xbfb8aa3b, v55
	v_exp_f32_e32 v57, v57
	v_lshlrev_b32_e32 v64, 16, v83
	v_and_b32_e32 v65, 0xffff0000, v83
	v_add_f32_e32 v57, 1.0, v57
	v_rcp_f32_e32 v59, v57
	s_nop 0
	v_pk_mul_f32 v[54:55], v[58:59], v[54:55]
	s_nop 0
	v_pk_mul_f32 v[48:49], v[48:49], v[54:55]
	s_nop 0
	v_cvt_pk_bf16_f32 v54, v48, v49
	v_mul_f32_e32 v48, 0xbfb8aa3b, v50
	v_lshlrev_b32_e32 v50, 16, v87
	v_mul_f32_e32 v55, 0xbfb8aa3b, v50
	v_exp_f32_e32 v55, v55
	v_mul_f32_e32 v49, 0xbfb8aa3b, v51
	v_and_b32_e32 v51, 0xffff0000, v87
	v_exp_f32_e32 v48, v48
	v_add_f32_e32 v55, 1.0, v55
	v_rcp_f32_e32 v58, v55
	v_mul_f32_e32 v55, 0xbfb8aa3b, v51
	v_exp_f32_e32 v49, v49
	v_exp_f32_e32 v55, v55
	v_add_f32_e32 v48, 1.0, v48
	v_rcp_f32_e32 v48, v48
	v_add_f32_e32 v49, 1.0, v49
	v_add_f32_e32 v55, 1.0, v55
	v_rcp_f32_e32 v49, v49
	v_rcp_f32_e32 v59, v55
	v_pk_mul_f32 v[48:49], v[48:49], v[64:65]
	v_pk_mul_f32 v[50:51], v[58:59], v[50:51]
	s_nop 0
	v_pk_mul_f32 v[48:49], v[48:49], v[50:51]
	s_nop 0
	v_cvt_pk_bf16_f32 v55, v48, v49
	v_add_u32_e32 v48, 0x8000, v56
	global_store_dwordx4 v48, v[52:55], s[60:61] offset:1536
	s_waitcnt vmcnt(4)
	v_lshlrev_b32_e32 v48, 16, v76
	v_and_b32_e32 v49, 0xffff0000, v76
	v_mul_f32_e32 v50, 0xbfb8aa3b, v48
	v_mul_f32_e32 v51, 0xbfb8aa3b, v49
	v_exp_f32_e32 v50, v50
	v_exp_f32_e32 v51, v51
	v_lshlrev_b32_e32 v52, 16, v72
	v_and_b32_e32 v53, 0xffff0000, v72
	v_add_f32_e32 v50, 1.0, v50
	v_add_f32_e32 v51, 1.0, v51
	v_rcp_f32_e32 v50, v50
	v_rcp_f32_e32 v51, v51
	v_pk_mul_f32 v[44:45], v[44:45], v[52:53]
	v_lshlrev_b32_e32 v52, 16, v73
	v_and_b32_e32 v53, 0xffff0000, v73
	v_pk_mul_f32 v[48:49], v[50:51], v[48:49]
	s_nop 0
	v_pk_mul_f32 v[44:45], v[44:45], v[48:49]
	v_lshlrev_b32_e32 v48, 16, v77
	v_cvt_pk_bf16_f32 v44, v44, v45
	v_mul_f32_e32 v45, 0xbfb8aa3b, v46
	v_exp_f32_e32 v45, v45
	v_and_b32_e32 v49, 0xffff0000, v77
	v_add_f32_e32 v45, 1.0, v45
	v_rcp_f32_e32 v46, v45
	v_mul_f32_e32 v45, 0xbfb8aa3b, v47
	v_exp_f32_e32 v45, v45
	s_nop 0
	v_add_f32_e32 v45, 1.0, v45
	v_rcp_f32_e32 v47, v45
	v_mul_f32_e32 v45, 0xbfb8aa3b, v48
	v_exp_f32_e32 v45, v45
	v_pk_mul_f32 v[46:47], v[46:47], v[52:53]
	v_add_f32_e32 v45, 1.0, v45
	v_rcp_f32_e32 v50, v45
	v_mul_f32_e32 v45, 0xbfb8aa3b, v49
	v_exp_f32_e32 v45, v45
	s_nop 0
	v_add_f32_e32 v45, 1.0, v45
	v_rcp_f32_e32 v51, v45
	s_nop 0
	v_pk_mul_f32 v[48:49], v[50:51], v[48:49]
	s_nop 0
	v_pk_mul_f32 v[46:47], v[46:47], v[48:49]
	v_lshlrev_b32_e32 v50, 16, v74
	v_cvt_pk_bf16_f32 v45, v46, v47
	v_lshlrev_b32_e32 v46, 16, v78
	v_and_b32_e32 v47, 0xffff0000, v78
	v_mul_f32_e32 v48, 0xbfb8aa3b, v46
	v_mul_f32_e32 v49, 0xbfb8aa3b, v47
	v_exp_f32_e32 v48, v48
	v_exp_f32_e32 v49, v49
	v_and_b32_e32 v51, 0xffff0000, v74
	v_pk_mul_f32 v[40:41], v[40:41], v[50:51]
	v_add_f32_e32 v48, 1.0, v48
	v_add_f32_e32 v49, 1.0, v49
	v_rcp_f32_e32 v48, v48
	v_rcp_f32_e32 v49, v49
	v_lshlrev_b32_e32 v50, 16, v75
	v_and_b32_e32 v51, 0xffff0000, v75
	v_pk_mul_f32 v[46:47], v[48:49], v[46:47]
	s_nop 0
	v_pk_mul_f32 v[40:41], v[40:41], v[46:47]
	s_nop 0
	v_cvt_pk_bf16_f32 v46, v40, v41
	v_mul_f32_e32 v40, 0xbfb8aa3b, v42
	v_lshlrev_b32_e32 v42, 16, v79
	v_mul_f32_e32 v47, 0xbfb8aa3b, v42
	v_exp_f32_e32 v47, v47
	v_mul_f32_e32 v41, 0xbfb8aa3b, v43
	v_and_b32_e32 v43, 0xffff0000, v79
	v_exp_f32_e32 v40, v40
	v_add_f32_e32 v47, 1.0, v47
	v_rcp_f32_e32 v48, v47
	v_mul_f32_e32 v47, 0xbfb8aa3b, v43
	v_exp_f32_e32 v41, v41
	v_exp_f32_e32 v47, v47
	v_add_f32_e32 v40, 1.0, v40
	v_rcp_f32_e32 v40, v40
	v_add_f32_e32 v41, 1.0, v41
	v_add_f32_e32 v47, 1.0, v47
	v_rcp_f32_e32 v41, v41
	v_rcp_f32_e32 v49, v47
	v_pk_mul_f32 v[40:41], v[40:41], v[50:51]
	v_pk_mul_f32 v[42:43], v[48:49], v[42:43]
	s_nop 0
	v_pk_mul_f32 v[40:41], v[40:41], v[42:43]
	s_nop 0
	v_cvt_pk_bf16_f32 v47, v40, v41
	v_add_u32_e32 v40, 0x10000, v56
	global_store_dwordx4 v40, v[44:47], s[60:61] offset:1536
	s_waitcnt vmcnt(3)
; __device__ __forceinline__ float sigm(float v) { return __builtin_amdgcn_rcpf(1.0f + __builtin_amdgcn_exp2f(-LOG2E * v)); }
; __device__ __forceinline__ float bf_lo(unsigned w) { return __uint_as_float(w << 16); }
; __device__ __forceinline__ float silu_f(float v) { return v * __builtin_amdgcn_rcpf(1.0f + __builtin_amdgcn_exp2f(-1.4426950408889634f * v)); }
; __device__ __forceinline__ float bf_hi(unsigned w) { return __uint_as_float(w & 0xffff0000u); }
; __device__ __forceinline__ unsigned cvt_pk_bf16(float lo, float hi) { f32x2_t v = {lo, hi}; bf16x2_t b = __builtin_convertvector(v, bf16x2_t); return __builtin_bit_cast(unsigned, b); }
;     __device__ __forceinline__ void operator()(const f32x4 (&acc)[2][2][4][2], const Unit& u, int wr, int wc, int fr, int fq) const {
;     ...
;                 for (int m = 0; m < 4; ++m) { const unsigned rl = rl0 + (unsigned)(ai * HALF + m * 16);
;                     ygv[m] = *(const u32x4*)(ygb + (rl * 256u + col) * 2u); sgv[m] = *(const u32x4*)(sgb + (rl * 512u + col) * 2u); }
; #pragma unroll
;                 for (int m = 0; m < 4; ++m) { const unsigned rl = rl0 + (unsigned)(ai * HALF + m * 16);
;                     const u32x4 yg = ygv[m], sg = sgv[m];
;                     const f32x4 v0 = acc[ai][bj][m][0], v1 = acc[ai][bj][m][1];
;                     u32x4 w;
;                     w.x = cvt_pk_bf16(bf_lo(yg.x) * sigm(v0[0]) * silu_f(bf_lo(sg.x)), bf_hi(yg.x) * sigm(v0[1]) * silu_f(bf_hi(sg.x)));
;                     w.y = cvt_pk_bf16(bf_lo(yg.y) * sigm(v0[2]) * silu_f(bf_lo(sg.y)), bf_hi(yg.y) * sigm(v0[3]) * silu_f(bf_hi(sg.y)));
;                     w.z = cvt_pk_bf16(bf_lo(yg.z) * sigm(v1[0]) * silu_f(bf_lo(sg.z)), bf_hi(yg.z) * sigm(v1[1]) * silu_f(bf_hi(sg.z)));
;                     w.w = cvt_pk_bf16(bf_lo(yg.w) * sigm(v1[2]) * silu_f(bf_lo(sg.w)), bf_hi(yg.w) * sigm(v1[3]) * silu_f(bf_hi(sg.w)));
;                     *(u32x4*)(yb + (rl * 1024u + col) * 2u) = w; }
	v_lshlrev_b32_e32 v40, 16, v68
	v_and_b32_e32 v41, 0xffff0000, v68
	v_mul_f32_e32 v42, 0xbfb8aa3b, v40
	v_mul_f32_e32 v43, 0xbfb8aa3b, v41
	v_exp_f32_e32 v42, v42
	v_exp_f32_e32 v43, v43
	v_lshlrev_b32_e32 v44, 16, v60
	v_and_b32_e32 v45, 0xffff0000, v60
	v_add_f32_e32 v42, 1.0, v42
	v_add_f32_e32 v43, 1.0, v43
	v_rcp_f32_e32 v42, v42
	v_rcp_f32_e32 v43, v43
	v_pk_mul_f32 v[36:37], v[36:37], v[44:45]
	v_lshlrev_b32_e32 v44, 16, v61
	v_and_b32_e32 v45, 0xffff0000, v61
	v_pk_mul_f32 v[40:41], v[42:43], v[40:41]
	s_nop 0
	v_pk_mul_f32 v[36:37], v[36:37], v[40:41]
	v_lshlrev_b32_e32 v40, 16, v69
	v_cvt_pk_bf16_f32 v36, v36, v37
	v_mul_f32_e32 v37, 0xbfb8aa3b, v38
	v_exp_f32_e32 v37, v37
	v_and_b32_e32 v41, 0xffff0000, v69
	v_add_f32_e32 v37, 1.0, v37
	v_rcp_f32_e32 v38, v37
	v_mul_f32_e32 v37, 0xbfb8aa3b, v39
	v_exp_f32_e32 v37, v37
	s_nop 0
	v_add_f32_e32 v37, 1.0, v37
	v_rcp_f32_e32 v39, v37
	v_mul_f32_e32 v37, 0xbfb8aa3b, v40
	v_exp_f32_e32 v37, v37
	v_pk_mul_f32 v[38:39], v[38:39], v[44:45]
	v_add_f32_e32 v37, 1.0, v37
	v_rcp_f32_e32 v42, v37
	v_mul_f32_e32 v37, 0xbfb8aa3b, v41
	v_exp_f32_e32 v37, v37
	s_nop 0
	v_add_f32_e32 v37, 1.0, v37
	v_rcp_f32_e32 v43, v37
	s_nop 0
	v_pk_mul_f32 v[40:41], v[42:43], v[40:41]
	s_nop 0
	v_pk_mul_f32 v[38:39], v[38:39], v[40:41]
	v_lshlrev_b32_e32 v42, 16, v62
	v_cvt_pk_bf16_f32 v37, v38, v39
	v_lshlrev_b32_e32 v38, 16, v70
	v_and_b32_e32 v39, 0xffff0000, v70
	v_mul_f32_e32 v40, 0xbfb8aa3b, v38
	v_mul_f32_e32 v41, 0xbfb8aa3b, v39
	v_exp_f32_e32 v40, v40
	v_exp_f32_e32 v41, v41
	v_and_b32_e32 v43, 0xffff0000, v62
	v_pk_mul_f32 v[32:33], v[32:33], v[42:43]
	v_add_f32_e32 v40, 1.0, v40
	v_add_f32_e32 v41, 1.0, v41
	v_rcp_f32_e32 v40, v40
	v_rcp_f32_e32 v41, v41
	v_lshlrev_b32_e32 v42, 16, v63
	v_and_b32_e32 v43, 0xffff0000, v63
	v_pk_mul_f32 v[38:39], v[40:41], v[38:39]
	s_nop 0
	v_pk_mul_f32 v[32:33], v[32:33], v[38:39]
	s_nop 0
	v_cvt_pk_bf16_f32 v38, v32, v33
	v_mul_f32_e32 v32, 0xbfb8aa3b, v34
	v_lshlrev_b32_e32 v34, 16, v71
	v_mul_f32_e32 v39, 0xbfb8aa3b, v34
	v_exp_f32_e32 v39, v39
	v_mul_f32_e32 v33, 0xbfb8aa3b, v35
	v_and_b32_e32 v35, 0xffff0000, v71
	v_exp_f32_e32 v32, v32
	v_add_f32_e32 v39, 1.0, v39
	v_rcp_f32_e32 v40, v39
	v_mul_f32_e32 v39, 0xbfb8aa3b, v35
	v_exp_f32_e32 v33, v33
	v_exp_f32_e32 v39, v39
	v_add_f32_e32 v32, 1.0, v32
	v_rcp_f32_e32 v32, v32
	v_add_f32_e32 v33, 1.0, v33
	v_add_f32_e32 v39, 1.0, v39
	v_rcp_f32_e32 v33, v33
	v_rcp_f32_e32 v41, v39
	v_pk_mul_f32 v[32:33], v[32:33], v[42:43]
	v_pk_mul_f32 v[34:35], v[40:41], v[34:35]
	s_nop 0
	v_pk_mul_f32 v[32:33], v[32:33], v[34:35]
	s_nop 0
	v_cvt_pk_bf16_f32 v39, v32, v33
	v_add_u32_e32 v32, 0x18000, v56
	global_store_dwordx4 v32, v[36:39], s[60:61] offset:1536
	s_nop 0
	v_lshlrev_b32_e32 v32, 9, v174
	v_add_u32_e32 v33, 0x10000, v32
	v_add_u32_e32 v34, v33, v98
	v_add_u32_e32 v33, v34, v33
	global_load_dwordx4 v[56:59], v34, s[62:63] nt
	global_load_dwordx4 v[60:63], v33, s[64:65] nt
	v_add_u32_e32 v33, 0x12000, v32
	v_add_u32_e32 v34, v33, v98
	v_add_u32_e32 v33, v34, v33
	global_load_dwordx4 v[48:51], v34, s[62:63] nt
	global_load_dwordx4 v[52:55], v33, s[64:65] nt
	v_add_u32_e32 v33, 0x14000, v32
	v_add_u32_e32 v36, 0x16000, v32
	v_add_u32_e32 v34, v33, v98
	v_add_u32_e32 v37, v36, v98
	v_add_u32_e32 v33, v34, v33
	v_add_u32_e32 v36, v37, v36
	global_load_dwordx4 v[40:43], v34, s[62:63] nt
	global_load_dwordx4 v[44:47], v33, s[64:65] nt
	s_waitcnt vmcnt(5)
	v_lshlrev_b32_e32 v68, 16, v56
	s_waitcnt vmcnt(4)
	v_lshlrev_b32_e32 v64, 16, v60
	v_and_b32_e32 v65, 0xffff0000, v60
	v_mul_f32_e32 v60, 0xbfb8aa3b, v64
	v_and_b32_e32 v69, 0xffff0000, v56
	v_mul_f32_e32 v56, 0xbfb8aa3b, v65
	v_exp_f32_e32 v60, v60
	v_exp_f32_e32 v56, v56
	v_pk_mul_f32 v[28:29], v[28:29], v[68:69]
	global_load_dwordx4 v[32:35], v37, s[62:63] nt
	v_add_f32_e32 v60, 1.0, v60
	v_add_f32_e32 v56, 1.0, v56
	v_rcp_f32_e32 v66, v60
	v_rcp_f32_e32 v67, v56
	v_lshlrev_b32_e32 v60, 16, v61
	v_and_b32_e32 v61, 0xffff0000, v61
	global_load_dwordx4 v[36:39], v36, s[64:65] nt
	v_pk_mul_f32 v[64:65], v[66:67], v[64:65]
	s_nop 0
	v_pk_mul_f32 v[28:29], v[28:29], v[64:65]
	v_lshlrev_b32_e32 v64, 16, v57
	v_cvt_pk_bf16_f32 v28, v28, v29
	v_mul_f32_e32 v29, 0xbfb8aa3b, v30
	v_exp_f32_e32 v29, v29
	v_and_b32_e32 v65, 0xffff0000, v57
	v_add_f32_e32 v29, 1.0, v29
	v_rcp_f32_e32 v30, v29
	v_mul_f32_e32 v29, 0xbfb8aa3b, v31
	v_exp_f32_e32 v29, v29
	s_nop 0
	v_add_f32_e32 v29, 1.0, v29
	v_rcp_f32_e32 v31, v29
	v_mul_f32_e32 v29, 0xbfb8aa3b, v60
	v_exp_f32_e32 v29, v29
	v_pk_mul_f32 v[30:31], v[30:31], v[64:65]
	v_add_f32_e32 v29, 1.0, v29
	v_rcp_f32_e32 v56, v29
	v_mul_f32_e32 v29, 0xbfb8aa3b, v61
	v_exp_f32_e32 v29, v29
	s_nop 0
	v_add_f32_e32 v29, 1.0, v29
	v_rcp_f32_e32 v57, v29
	s_nop 0
	v_pk_mul_f32 v[56:57], v[56:57], v[60:61]
	s_nop 0
	v_pk_mul_f32 v[30:31], v[30:31], v[56:57]
	v_lshlrev_b32_e32 v60, 16, v58
	v_cvt_pk_bf16_f32 v29, v30, v31
	v_lshlrev_b32_e32 v30, 16, v62
	v_and_b32_e32 v31, 0xffff0000, v62
	v_mul_f32_e32 v56, 0xbfb8aa3b, v30
	v_mul_f32_e32 v57, 0xbfb8aa3b, v31
	v_exp_f32_e32 v56, v56
	v_exp_f32_e32 v57, v57
	v_and_b32_e32 v61, 0xffff0000, v58
	v_pk_mul_f32 v[24:25], v[24:25], v[60:61]
	v_add_f32_e32 v56, 1.0, v56
	v_add_f32_e32 v57, 1.0, v57
	v_rcp_f32_e32 v56, v56
	v_rcp_f32_e32 v57, v57
	v_lshlrev_b32_e32 v58, 16, v59
	v_and_b32_e32 v59, 0xffff0000, v59
	v_pk_mul_f32 v[30:31], v[56:57], v[30:31]
	s_nop 0
	v_pk_mul_f32 v[24:25], v[24:25], v[30:31]
	s_nop 0
	v_cvt_pk_bf16_f32 v30, v24, v25
	v_mul_f32_e32 v24, 0xbfb8aa3b, v26
	v_lshlrev_b32_e32 v26, 16, v63
	v_mul_f32_e32 v31, 0xbfb8aa3b, v26
	v_exp_f32_e32 v31, v31
	v_mul_f32_e32 v25, 0xbfb8aa3b, v27
	v_and_b32_e32 v27, 0xffff0000, v63
	v_exp_f32_e32 v24, v24
	v_add_f32_e32 v31, 1.0, v31
	v_rcp_f32_e32 v56, v31
	v_mul_f32_e32 v31, 0xbfb8aa3b, v27
	v_exp_f32_e32 v25, v25
	v_exp_f32_e32 v31, v31
	v_add_f32_e32 v24, 1.0, v24
	v_rcp_f32_e32 v24, v24
	v_add_f32_e32 v25, 1.0, v25
	v_add_f32_e32 v31, 1.0, v31
	v_rcp_f32_e32 v25, v25
	v_rcp_f32_e32 v57, v31
	v_pk_mul_f32 v[24:25], v[24:25], v[58:59]
	v_pk_mul_f32 v[26:27], v[56:57], v[26:27]
	s_nop 0
	v_pk_mul_f32 v[24:25], v[24:25], v[26:27]
	s_waitcnt vmcnt(4)
; __device__ __forceinline__ float sigm(float v) { return __builtin_amdgcn_rcpf(1.0f + __builtin_amdgcn_exp2f(-LOG2E * v)); }
; __device__ __forceinline__ float bf_lo(unsigned w) { return __uint_as_float(w << 16); }
; __device__ __forceinline__ float silu_f(float v) { return v * __builtin_amdgcn_rcpf(1.0f + __builtin_amdgcn_exp2f(-1.4426950408889634f * v)); }
; __device__ __forceinline__ float bf_hi(unsigned w) { return __uint_as_float(w & 0xffff0000u); }
; __device__ __forceinline__ unsigned cvt_pk_bf16(float lo, float hi) { f32x2_t v = {lo, hi}; bf16x2_t b = __builtin_convertvector(v, bf16x2_t); return __builtin_bit_cast(unsigned, b); }
;     __device__ __forceinline__ void operator()(const f32x4 (&acc)[2][2][4][2], const Unit& u, int wr, int wc, int fr, int fq) const {
;     ...
;                 for (int m = 0; m < 4; ++m) { const unsigned rl = rl0 + (unsigned)(ai * HALF + m * 16);
;                     const u32x4 yg = ygv[m], sg = sgv[m];
;                     const f32x4 v0 = acc[ai][bj][m][0], v1 = acc[ai][bj][m][1];
;                     u32x4 w;
;                     w.x = cvt_pk_bf16(bf_lo(yg.x) * sigm(v0[0]) * silu_f(bf_lo(sg.x)), bf_hi(yg.x) * sigm(v0[1]) * silu_f(bf_hi(sg.x)));
;                     w.y = cvt_pk_bf16(bf_lo(yg.y) * sigm(v0[2]) * silu_f(bf_lo(sg.y)), bf_hi(yg.y) * sigm(v0[3]) * silu_f(bf_hi(sg.y)));
;                     w.z = cvt_pk_bf16(bf_lo(yg.z) * sigm(v1[0]) * silu_f(bf_lo(sg.z)), bf_hi(yg.z) * sigm(v1[1]) * silu_f(bf_hi(sg.z)));
;                     w.w = cvt_pk_bf16(bf_lo(yg.w) * sigm(v1[2]) * silu_f(bf_lo(sg.w)), bf_hi(yg.w) * sigm(v1[3]) * silu_f(bf_hi(sg.w)));
;                     *(u32x4*)(yb + (rl * 1024u + col) * 2u) = w; }
	v_lshlrev_b32_e32 v26, 16, v52
	v_cvt_pk_bf16_f32 v31, v24, v25
	v_lshl_add_u32 v24, v174, 11, v98
	v_add_u32_e32 v25, 0x40000, v24
	global_store_dwordx4 v25, v[28:31], s[60:61] offset:1536
	v_mul_f32_e32 v25, 0xbfb8aa3b, v26
	v_exp_f32_e32 v25, v25
	v_and_b32_e32 v27, 0xffff0000, v52
	v_lshlrev_b32_e32 v30, 16, v48
	v_and_b32_e32 v31, 0xffff0000, v48
	v_add_f32_e32 v25, 1.0, v25
	v_rcp_f32_e32 v28, v25
	v_mul_f32_e32 v25, 0xbfb8aa3b, v27
	v_exp_f32_e32 v25, v25
	v_pk_mul_f32 v[20:21], v[20:21], v[30:31]
	v_lshlrev_b32_e32 v30, 16, v49
	v_and_b32_e32 v31, 0xffff0000, v49
	v_add_f32_e32 v25, 1.0, v25
	v_rcp_f32_e32 v29, v25
	s_nop 0
	v_pk_mul_f32 v[26:27], v[28:29], v[26:27]
	s_nop 0
	v_pk_mul_f32 v[20:21], v[20:21], v[26:27]
	v_lshlrev_b32_e32 v26, 16, v53
	v_cvt_pk_bf16_f32 v20, v20, v21
	v_mul_f32_e32 v21, 0xbfb8aa3b, v22
	v_exp_f32_e32 v21, v21
	v_and_b32_e32 v27, 0xffff0000, v53
	v_add_f32_e32 v21, 1.0, v21
	v_rcp_f32_e32 v22, v21
	v_mul_f32_e32 v21, 0xbfb8aa3b, v23
	v_exp_f32_e32 v21, v21
	s_nop 0
	v_add_f32_e32 v21, 1.0, v21
	v_rcp_f32_e32 v23, v21
	v_mul_f32_e32 v21, 0xbfb8aa3b, v26
	v_exp_f32_e32 v21, v21
	v_pk_mul_f32 v[22:23], v[22:23], v[30:31]
	v_add_f32_e32 v21, 1.0, v21
	v_rcp_f32_e32 v28, v21
	v_mul_f32_e32 v21, 0xbfb8aa3b, v27
	v_exp_f32_e32 v21, v21
	s_nop 0
	v_add_f32_e32 v21, 1.0, v21
	v_rcp_f32_e32 v29, v21
	s_nop 0
	v_pk_mul_f32 v[26:27], v[28:29], v[26:27]
	s_nop 0
	v_pk_mul_f32 v[22:23], v[22:23], v[26:27]
	v_lshlrev_b32_e32 v28, 16, v50
	v_cvt_pk_bf16_f32 v21, v22, v23
	v_lshlrev_b32_e32 v22, 16, v54
	v_mul_f32_e32 v25, 0xbfb8aa3b, v22
	v_exp_f32_e32 v25, v25
	v_and_b32_e32 v23, 0xffff0000, v54
	v_and_b32_e32 v29, 0xffff0000, v50
	v_pk_mul_f32 v[16:17], v[16:17], v[28:29]
	v_add_f32_e32 v25, 1.0, v25
	v_rcp_f32_e32 v26, v25
	v_mul_f32_e32 v25, 0xbfb8aa3b, v23
	v_exp_f32_e32 v25, v25
	v_lshlrev_b32_e32 v28, 16, v51
	v_and_b32_e32 v29, 0xffff0000, v51
	v_add_f32_e32 v25, 1.0, v25
	v_rcp_f32_e32 v27, v25
	s_nop 0
	v_pk_mul_f32 v[22:23], v[26:27], v[22:23]
	s_nop 0
	v_pk_mul_f32 v[16:17], v[16:17], v[22:23]
	s_nop 0
	v_cvt_pk_bf16_f32 v22, v16, v17
	v_mul_f32_e32 v16, 0xbfb8aa3b, v18
	v_lshlrev_b32_e32 v18, 16, v55
	v_mul_f32_e32 v23, 0xbfb8aa3b, v18
	v_exp_f32_e32 v23, v23
	v_mul_f32_e32 v17, 0xbfb8aa3b, v19
	v_and_b32_e32 v19, 0xffff0000, v55
	v_exp_f32_e32 v16, v16
	v_add_f32_e32 v23, 1.0, v23
	v_rcp_f32_e32 v26, v23
	v_mul_f32_e32 v23, 0xbfb8aa3b, v19
	v_exp_f32_e32 v17, v17
	v_exp_f32_e32 v23, v23
	v_add_f32_e32 v16, 1.0, v16
	v_rcp_f32_e32 v16, v16
	v_add_f32_e32 v17, 1.0, v17
	v_add_f32_e32 v23, 1.0, v23
	v_rcp_f32_e32 v17, v17
	v_rcp_f32_e32 v27, v23
	v_pk_mul_f32 v[16:17], v[16:17], v[28:29]
	v_pk_mul_f32 v[18:19], v[26:27], v[18:19]
	s_nop 0
	v_pk_mul_f32 v[16:17], v[16:17], v[18:19]
	s_nop 0
	v_cvt_pk_bf16_f32 v23, v16, v17
	v_add_u32_e32 v16, 0x48000, v24
	global_store_dwordx4 v16, v[20:23], s[60:61] offset:1536
	s_waitcnt vmcnt(4)
	v_lshlrev_b32_e32 v16, 16, v44
	v_and_b32_e32 v17, 0xffff0000, v44
	v_mul_f32_e32 v18, 0xbfb8aa3b, v16
	v_mul_f32_e32 v19, 0xbfb8aa3b, v17
	v_exp_f32_e32 v18, v18
	v_exp_f32_e32 v19, v19
	v_lshlrev_b32_e32 v20, 16, v40
	v_and_b32_e32 v21, 0xffff0000, v40
	v_add_f32_e32 v18, 1.0, v18
	v_add_f32_e32 v19, 1.0, v19
	v_rcp_f32_e32 v18, v18
	v_rcp_f32_e32 v19, v19
	v_pk_mul_f32 v[12:13], v[12:13], v[20:21]
	v_lshlrev_b32_e32 v20, 16, v41
	v_and_b32_e32 v21, 0xffff0000, v41
	v_pk_mul_f32 v[16:17], v[18:19], v[16:17]
	s_nop 0
	v_pk_mul_f32 v[12:13], v[12:13], v[16:17]
	v_lshlrev_b32_e32 v16, 16, v45
	v_cvt_pk_bf16_f32 v12, v12, v13
	v_mul_f32_e32 v13, 0xbfb8aa3b, v14
	v_exp_f32_e32 v13, v13
	v_and_b32_e32 v17, 0xffff0000, v45
	v_add_f32_e32 v13, 1.0, v13
	v_rcp_f32_e32 v14, v13
	v_mul_f32_e32 v13, 0xbfb8aa3b, v15
	v_exp_f32_e32 v13, v13
	s_nop 0
	v_add_f32_e32 v13, 1.0, v13
	v_rcp_f32_e32 v15, v13
	v_mul_f32_e32 v13, 0xbfb8aa3b, v16
	v_exp_f32_e32 v13, v13
	v_pk_mul_f32 v[14:15], v[14:15], v[20:21]
	v_add_f32_e32 v13, 1.0, v13
	v_rcp_f32_e32 v18, v13
	v_mul_f32_e32 v13, 0xbfb8aa3b, v17
	v_exp_f32_e32 v13, v13
	s_nop 0
	v_add_f32_e32 v13, 1.0, v13
	v_rcp_f32_e32 v19, v13
	s_nop 0
	v_pk_mul_f32 v[16:17], v[18:19], v[16:17]
	s_nop 0
	v_pk_mul_f32 v[14:15], v[14:15], v[16:17]
	v_lshlrev_b32_e32 v18, 16, v42
	v_cvt_pk_bf16_f32 v13, v14, v15
	v_lshlrev_b32_e32 v14, 16, v46
	v_and_b32_e32 v15, 0xffff0000, v46
	v_mul_f32_e32 v16, 0xbfb8aa3b, v14
	v_mul_f32_e32 v17, 0xbfb8aa3b, v15
	v_exp_f32_e32 v16, v16
	v_exp_f32_e32 v17, v17
	v_and_b32_e32 v19, 0xffff0000, v42
	v_pk_mul_f32 v[8:9], v[8:9], v[18:19]
	v_add_f32_e32 v16, 1.0, v16
	v_add_f32_e32 v17, 1.0, v17
	v_rcp_f32_e32 v16, v16
	v_rcp_f32_e32 v17, v17
	v_lshlrev_b32_e32 v18, 16, v43
	v_and_b32_e32 v19, 0xffff0000, v43
	v_pk_mul_f32 v[14:15], v[16:17], v[14:15]
	s_nop 0
	v_pk_mul_f32 v[8:9], v[8:9], v[14:15]
	s_nop 0
	v_cvt_pk_bf16_f32 v14, v8, v9
	v_mul_f32_e32 v8, 0xbfb8aa3b, v10
	v_lshlrev_b32_e32 v10, 16, v47
	v_mul_f32_e32 v15, 0xbfb8aa3b, v10
	v_exp_f32_e32 v15, v15
	v_mul_f32_e32 v9, 0xbfb8aa3b, v11
	v_and_b32_e32 v11, 0xffff0000, v47
	v_exp_f32_e32 v8, v8
	v_add_f32_e32 v15, 1.0, v15
	v_rcp_f32_e32 v16, v15
	v_mul_f32_e32 v15, 0xbfb8aa3b, v11
	v_exp_f32_e32 v9, v9
	v_exp_f32_e32 v15, v15
	v_add_f32_e32 v8, 1.0, v8
	v_rcp_f32_e32 v8, v8
	v_add_f32_e32 v9, 1.0, v9
	v_add_f32_e32 v15, 1.0, v15
	v_rcp_f32_e32 v9, v9
	v_rcp_f32_e32 v17, v15
	v_pk_mul_f32 v[8:9], v[8:9], v[18:19]
	v_pk_mul_f32 v[10:11], v[16:17], v[10:11]
	s_nop 0
	v_pk_mul_f32 v[8:9], v[8:9], v[10:11]
	s_nop 0
	v_cvt_pk_bf16_f32 v15, v8, v9
	v_add_u32_e32 v8, 0x50000, v24
	global_store_dwordx4 v8, v[12:15], s[60:61] offset:1536
	s_waitcnt vmcnt(3)
; __device__ __forceinline__ float sigm(float v) { return __builtin_amdgcn_rcpf(1.0f + __builtin_amdgcn_exp2f(-LOG2E * v)); }
; __device__ __forceinline__ float bf_lo(unsigned w) { return __uint_as_float(w << 16); }
; __device__ __forceinline__ float silu_f(float v) { return v * __builtin_amdgcn_rcpf(1.0f + __builtin_amdgcn_exp2f(-1.4426950408889634f * v)); }
; __device__ __forceinline__ float bf_hi(unsigned w) { return __uint_as_float(w & 0xffff0000u); }
; #define PG8_BAR __builtin_amdgcn_s_barrier()
;     __device__ __forceinline__ void operator()(const f32x4 (&acc)[2][2][4][2], const Unit& u, int wr, int wc, int fr, int fq) const {
;     ...
;                 for (int m = 0; m < 4; ++m) { const unsigned rl = rl0 + (unsigned)(ai * HALF + m * 16);
;                     const u32x4 yg = ygv[m], sg = sgv[m];
;                     const f32x4 v0 = acc[ai][bj][m][0], v1 = acc[ai][bj][m][1];
;                     u32x4 w;
;                     w.x = cvt_pk_bf16(bf_lo(yg.x) * sigm(v0[0]) * silu_f(bf_lo(sg.x)), bf_hi(yg.x) * sigm(v0[1]) * silu_f(bf_hi(sg.x)));
;                     w.y = cvt_pk_bf16(bf_lo(yg.y) * sigm(v0[2]) * silu_f(bf_lo(sg.y)), bf_hi(yg.y) * sigm(v0[3]) * silu_f(bf_hi(sg.y)));
;                     w.z = cvt_pk_bf16(bf_lo(yg.z) * sigm(v1[0]) * silu_f(bf_lo(sg.z)), bf_hi(yg.z) * sigm(v1[1]) * silu_f(bf_hi(sg.z)));
;                     w.w = cvt_pk_bf16(bf_lo(yg.w) * sigm(v1[2]) * silu_f(bf_lo(sg.w)), bf_hi(yg.w) * sigm(v1[3]) * silu_f(bf_hi(sg.w)));
;                     *(u32x4*)(yb + (rl * 1024u + col) * 2u) = w; }
; template <class Epi, class Sched, bool ALIGN_EPI = false, bool SP2 = false>
; __device__ __forceinline__ void gemm_phase(PG8_LAS unsigned char* lds, const Gemm g, const Sched& S, const Epi& E) {
;     ...
;         if constexpr (ALIGN_EPI) { if (wr == 0) PG8_BAR; }
;         if constexpr (!Epi::AFTER_DRAIN) { E(acc, cur, wr, wc, fr, fq); S.done(cur); }
;         if (!has_next) break;
;         if constexpr (Epi::ACC_INIT) E.acc_init(ini, nxt);
; #pragma unroll
;         for (int a = 0; a < 2; ++a)
; #pragma unroll
;             for (int b = 0; b < 2; ++b)
; #pragma unroll
;                 for (int m = 0; m < 4; ++m)
; #pragma unroll
;                     for (int n = 0; n < 2; ++n) acc[a][b][m][n] = ini[b][n];
;         cur = nxt; cA = nA; cB = nB; ++ui;
;         if constexpr (ALIGN_EPI) { if (wr == 1) PG8_BAR; }
	v_lshlrev_b32_e32 v8, 16, v36
	v_and_b32_e32 v9, 0xffff0000, v36
	v_mul_f32_e32 v10, 0xbfb8aa3b, v8
	v_mul_f32_e32 v11, 0xbfb8aa3b, v9
	v_exp_f32_e32 v10, v10
	v_exp_f32_e32 v11, v11
	v_lshlrev_b32_e32 v12, 16, v32
	v_and_b32_e32 v13, 0xffff0000, v32
	v_add_f32_e32 v10, 1.0, v10
	v_add_f32_e32 v11, 1.0, v11
	v_rcp_f32_e32 v10, v10
	v_rcp_f32_e32 v11, v11
	v_pk_mul_f32 v[4:5], v[4:5], v[12:13]
	v_lshlrev_b32_e32 v12, 16, v33
	v_and_b32_e32 v13, 0xffff0000, v33
	v_pk_mul_f32 v[8:9], v[10:11], v[8:9]
	s_nop 0
	v_pk_mul_f32 v[4:5], v[4:5], v[8:9]
	v_lshlrev_b32_e32 v8, 16, v37
	v_cvt_pk_bf16_f32 v4, v4, v5
	v_mul_f32_e32 v5, 0xbfb8aa3b, v6
	v_exp_f32_e32 v5, v5
	v_and_b32_e32 v9, 0xffff0000, v37
	v_add_f32_e32 v5, 1.0, v5
	v_rcp_f32_e32 v6, v5
	v_mul_f32_e32 v5, 0xbfb8aa3b, v7
	v_exp_f32_e32 v5, v5
	s_nop 0
	v_add_f32_e32 v5, 1.0, v5
	v_rcp_f32_e32 v7, v5
	v_mul_f32_e32 v5, 0xbfb8aa3b, v8
	v_exp_f32_e32 v5, v5
	v_pk_mul_f32 v[6:7], v[6:7], v[12:13]
	v_add_f32_e32 v5, 1.0, v5
	v_rcp_f32_e32 v10, v5
	v_mul_f32_e32 v5, 0xbfb8aa3b, v9
	v_exp_f32_e32 v5, v5
	s_nop 0
	v_add_f32_e32 v5, 1.0, v5
	v_rcp_f32_e32 v11, v5
	s_nop 0
	v_pk_mul_f32 v[8:9], v[10:11], v[8:9]
	s_nop 0
	v_pk_mul_f32 v[6:7], v[6:7], v[8:9]
	v_lshlrev_b32_e32 v10, 16, v34
	v_cvt_pk_bf16_f32 v5, v6, v7
	v_lshlrev_b32_e32 v6, 16, v38
	v_and_b32_e32 v7, 0xffff0000, v38
	v_mul_f32_e32 v8, 0xbfb8aa3b, v6
	v_mul_f32_e32 v9, 0xbfb8aa3b, v7
	v_exp_f32_e32 v8, v8
	v_exp_f32_e32 v9, v9
	v_and_b32_e32 v11, 0xffff0000, v34
	v_pk_mul_f32 v[0:1], v[0:1], v[10:11]
	v_add_f32_e32 v8, 1.0, v8
	v_add_f32_e32 v9, 1.0, v9
	v_rcp_f32_e32 v8, v8
	v_rcp_f32_e32 v9, v9
	v_lshlrev_b32_e32 v10, 16, v35
	v_and_b32_e32 v11, 0xffff0000, v35
	v_pk_mul_f32 v[6:7], v[8:9], v[6:7]
	s_nop 0
	v_pk_mul_f32 v[0:1], v[0:1], v[6:7]
	s_nop 0
	v_cvt_pk_bf16_f32 v6, v0, v1
	v_mul_f32_e32 v0, 0xbfb8aa3b, v2
	v_lshlrev_b32_e32 v2, 16, v39
	v_mul_f32_e32 v7, 0xbfb8aa3b, v2
	v_exp_f32_e32 v7, v7
	v_mul_f32_e32 v1, 0xbfb8aa3b, v3
	v_and_b32_e32 v3, 0xffff0000, v39
	v_exp_f32_e32 v0, v0
	v_add_f32_e32 v7, 1.0, v7
	v_rcp_f32_e32 v8, v7
	v_mul_f32_e32 v7, 0xbfb8aa3b, v3
	v_exp_f32_e32 v1, v1
	v_exp_f32_e32 v7, v7
	v_add_f32_e32 v0, 1.0, v0
	v_rcp_f32_e32 v0, v0
	v_add_f32_e32 v1, 1.0, v1
	v_add_f32_e32 v7, 1.0, v7
	v_rcp_f32_e32 v1, v1
	v_rcp_f32_e32 v9, v7
	v_pk_mul_f32 v[0:1], v[0:1], v[10:11]
	v_pk_mul_f32 v[2:3], v[8:9], v[2:3]
	s_nop 0
	v_pk_mul_f32 v[0:1], v[0:1], v[2:3]
	s_nop 0
	v_cvt_pk_bf16_f32 v7, v0, v1
	v_add_u32_e32 v0, 0x58000, v24
	global_store_dwordx4 v0, v[4:7], s[60:61] offset:1536
	s_mov_b64 s[60:61], -1
	s_cbranch_vccnz .LBB0_68
	v_mov_b32_e32 v0, v212
	s_nop 0
	v_readfirstlane_b32 s0, v0
	s_lshl_b32 s0, s0, 1
	s_and_b32 s0, s0, 0x180
	s_add_u32 s16, s25, s0
	v_lshlrev_b32_e32 v0, 1, v0
	s_addc_u32 s17, s31, 0
	v_and_b32_e32 v4, 0x60, v0
	global_load_dwordx4 v[60:63], v4, s[16:17] offset:16
	global_load_dwordx4 v[68:71], v4, s[16:17]
	global_load_dwordx4 v[0:3], v4, s[16:17] offset:528
	s_nop 0
	global_load_dwordx4 v[4:7], v4, s[16:17] offset:512
	v_readlane_b32 s16, v252, 52
	v_readlane_b32 s17, v252, 53
	s_andn2_b64 vcc, exec, s[16:17]
	s_cbranch_vccnz .LBB0_67
	s_barrier
	s_branch .LBB0_67

; #define POOL_FETCH(gi_) do { _Pragma("unroll") for (int k_ = 0; k_ < 3; ++k_) { const int it_ = tid + 512 * k_; const int r_ = it_ >> 3, ch_ = it_ & 7; pre[k_] = (u32x4){0u, 0u, 0u, 0u}; \
;         if (it_ < 143 * 8 && !(pos0 == 0 && r_ < 15)) pre[k_] = *(const u32x4*)(ZA + (size_t)(t0 - 15 + r_) * 512 + (gi_) * 64 + ch_ * 8); } } while (0)
; __device__ __forceinline__ void pool_tile(const Ctx& c, int l, int tile) {
;     ...
;     const int t0 = tile * 128, pos0 = t0 & (SEQ - 1);
;     u32x4 pre[3];
;     ...
;     POOL_FETCH(0);
.LBB0_329:
	s_lshl_b32 s13, s6, 7
	s_and_b32 s12, s13, 0xf80
	s_cmp_eq_u32 s12, 0
	s_cselect_b64 s[66:67], -1, 0
	s_add_i32 s12, s13, -15
	s_and_b64 s[16:17], s[40:41], s[66:67]
	v_add_u32_e32 v0, s12, v114
	s_nor_b64 s[60:61], s[38:39], s[16:17]
	v_mov_b32_e32 v16, 0
	v_ashrrev_i32_e32 v1, 31, v0
	v_mov_b32_e32 v20, 0
	v_mov_b32_e32 v21, 0
	v_mov_b32_e32 v22, 0
	v_mov_b32_e32 v23, 0
	s_and_saveexec_b64 s[64:65], s[60:61]
	s_cbranch_execz .LBB0_331
	v_lshlrev_b64 v[2:3], 10, v[0:1]
	v_lshl_add_u64 v[2:3], v[30:31], 0, v[2:3]
	global_load_dwordx4 v[20:23], v[2:3], off nt
.LBB0_331:
	s_or_b64 exec, exec, s[64:65]
	s_and_b64 s[16:17], s[44:45], s[66:67]
	v_add_u32_e32 v2, s12, v115
	s_nor_b64 s[64:65], s[42:43], s[16:17]
	v_ashrrev_i32_e32 v3, 31, v2
	v_mov_b32_e32 v17, 0
	v_mov_b32_e32 v18, 0
	v_mov_b32_e32 v19, 0
	s_and_saveexec_b64 s[68:69], s[64:65]
	s_cbranch_execz .LBB0_333
	v_lshlrev_b64 v[4:5], 10, v[2:3]
	v_lshl_add_u64 v[4:5], v[30:31], 0, v[4:5]
	global_load_dwordx4 v[16:19], v[4:5], off nt
.LBB0_333:
	s_or_b64 exec, exec, s[68:69]
	v_add_u32_e32 v4, s12, v116
	s_and_b64 s[16:17], s[48:49], s[66:67]
	v_ashrrev_i32_e32 v5, 31, v4
	s_nor_b64 s[66:67], s[46:47], s[16:17]
	v_lshlrev_b64 v[38:39], 10, v[4:5]
	v_mov_b32_e32 v24, 0
	v_mov_b32_e32 v25, 0
	v_mov_b32_e32 v26, 0
	v_mov_b32_e32 v27, 0
	s_and_saveexec_b64 s[68:69], s[66:67]
	s_cbranch_execz .LBB0_335
	v_lshl_add_u64 v[4:5], v[30:31], 0, v[38:39]
	global_load_dwordx4 v[24:27], v[4:5], off nt

; __device__ __forceinline__ float bf_lo(unsigned w) { return __uint_as_float(w << 16); }
; __device__ __forceinline__ float bf_hi(unsigned w) { return __uint_as_float(w & 0xffff0000u); }
; #define POOL_FETCH(gi_) do { _Pragma("unroll") for (int k_ = 0; k_ < 3; ++k_) { const int it_ = tid + 512 * k_; const int r_ = it_ >> 3, ch_ = it_ & 7; pre[k_] = (u32x4){0u, 0u, 0u, 0u}; \
;         if (it_ < 143 * 8 && !(pos0 == 0 && r_ < 15)) pre[k_] = *(const u32x4*)(ZA + (size_t)(t0 - 15 + r_) * 512 + (gi_) * 64 + ch_ * 8); } } while (0)
; __device__ __forceinline__ void pool_tile(const Ctx& c, int l, int tile) {
;     ...
;     POOL_FETCH(0);
; #pragma unroll 1
;     for (int gi = 0; gi < 4; ++gi) {
;         const int w = 2 << gi;
; #pragma unroll
;         for (int k = 0; k < 3; ++k) { const int it = tid + 512 * k; const int r = it >> 3, ch = it & 7;
;             if (it < 143 * 8) { const u32x4 q = pre[k];
;                 *(f32x4*)(U + r * 64 + ch * 8) = (f32x4){bf_lo(q.x), bf_hi(q.x), bf_lo(q.y), bf_hi(q.y)}; *(f32x4*)(U + r * 64 + ch * 8 + 4) = (f32x4){bf_lo(q.z), bf_hi(q.z), bf_lo(q.w), bf_hi(q.w)}; } }
;         __syncthreads();
;         if (gi < 3) POOL_FETCH(gi + 1);
.LBB0_340:
	s_or_b64 exec, exec, s[68:69]
	s_cmp_lg_u32 s13, 3
	s_waitcnt lgkmcnt(0)
	s_barrier
	s_cbranch_scc0 .LBB0_348
	s_lshl_b32 s16, s13, 7
	s_add_u32 s68, s90, s16
	s_addc_u32 s69, s91, 0
	s_waitcnt vmcnt(0)
	v_mov_b32_e32 v16, 0
	v_lshlrev_b32_e32 v96, 1, v28
	v_mov_b32_e32 v20, 0
	v_mov_b32_e32 v21, 0
	v_mov_b32_e32 v22, 0
	v_mov_b32_e32 v23, 0
	s_and_saveexec_b64 s[70:71], s[60:61]
	s_cbranch_execz .LBB0_343
	v_lshl_add_u64 v[0:1], s[68:69], 0, v[40:41]
	v_lshl_add_u64 v[0:1], v[0:1], 0, v[96:97]
	global_load_dwordx4 v[20:23], v[0:1], off offset:128 nt
.LBB0_343:
	s_or_b64 exec, exec, s[70:71]
	v_mov_b32_e32 v17, 0
	v_mov_b32_e32 v18, 0
	v_mov_b32_e32 v19, 0
	s_and_saveexec_b64 s[70:71], s[64:65]
	s_cbranch_execz .LBB0_345
	v_lshl_add_u64 v[0:1], s[68:69], 0, v[42:43]
	v_lshl_add_u64 v[0:1], v[0:1], 0, v[96:97]
	global_load_dwordx4 v[16:19], v[0:1], off offset:128 nt
.LBB0_345:
	s_or_b64 exec, exec, s[70:71]
	v_mov_b32_e32 v27, 0
	v_mov_b32_e32 v26, 0
	v_mov_b32_e32 v25, 0
	v_mov_b32_e32 v24, 0
	s_and_saveexec_b64 s[70:71], s[66:67]
	s_cbranch_execz .LBB0_347
	v_lshl_add_u64 v[0:1], s[68:69], 0, v[38:39]
	v_lshl_add_u64 v[0:1], v[0:1], 0, v[96:97]
	global_load_dwordx4 v[24:27], v[0:1], off offset:128 nt

; __device__ __forceinline__ void pool_tile(const Ctx& c, int l, int tile) {
;     ...
;             const int ch = tid & 63, i0 = (tid >> 6) * 16;
;             float s = 0.f;
;             for (int j = 1; j < w; ++j) s += U[(15 + i0 - j) * 64 + ch];
;             for (int i = i0; i < i0 + 16; ++i) {
;                 const float cur = U[(15 + i) * 64 + ch]; s += cur;
;                 const int cnt = min(pos0 + i + 1, w);
;                 Pm[i * 65 + ch] = s / (float)cnt - cur;
;                 s -= U[(15 + i - (w - 1)) * 64 + ch];
;             }
;         }
;         __syncthreads();
;         {
;             const int rt = wave >> 1, ct = wave & 1, li = lane & 31, lh = lane >> 5;
;             const int j = 32 * ct + li;
;             unsigned short gv[16];
; #pragma unroll
;             for (int r = 0; r < 16; ++r) { const int i = (r & 3) + 8 * (r >> 2) + 4 * lh; gv[r] = ZA[(size_t)(t0 + 32 * rt + i) * 512 + 256 + gi * 64 + j]; }
;             const float* pw = c.inp(IN_POOLW) + (size_t)(l * 4 + gi) * 4096 + j;
;             const float sc = c.inp(IN_POOLS)[l * 256 + gi * 64 + j];
;             f32x16 acc = {};
.LBB0_351:
	ds_read_b32 v4, v1
	v_add3_u32 v5, s12, v0, 2
	v_min_i32_e32 v5, s16, v5
	v_cvt_f32_i32_e32 v5, v5
	v_add_u32_e32 v0, 1, v0
	s_waitcnt lgkmcnt(0)
	v_add_f32_e32 v3, v3, v4
	v_div_scale_f32 v6, s[20:21], v5, v5, v3
	v_rcp_f32_e32 v7, v6
	s_nop 0
	v_fma_f32 v8, -v6, v7, 1.0
	v_fmac_f32_e32 v7, v8, v7
	v_div_scale_f32 v8, vcc, v3, v5, v3
	v_mul_f32_e32 v9, v8, v7
	v_fma_f32 v10, -v6, v9, v8
	v_fmac_f32_e32 v9, v10, v7
	v_fma_f32 v6, -v6, v9, v8
	v_div_fmas_f32 v6, v6, v7, v9
	v_div_fixup_f32 v5, v6, v5, v3
	v_sub_f32_e32 v4, v5, v4
	ds_write_b32 v2, v4
	v_add_u32_e32 v4, s17, v1
	ds_read_b32 v4, v4 offset:256
	v_cmp_ge_i32_e32 vcc, v0, v117
	v_add_u32_e32 v2, 0x104, v2
	v_add_u32_e32 v1, 0x100, v1
	s_or_b64 s[68:69], vcc, s[68:69]
	s_waitcnt lgkmcnt(0)
	v_sub_f32_e32 v3, v3, v4
	s_andn2_b64 exec, exec, s[68:69]
	s_cbranch_execnz .LBB0_351
	s_or_b64 exec, exec, s[68:69]
	s_lshl_b32 s34, s13, 7
	v_lshl_add_u64 v[0:1], v[32:33], 0, s[34:35]
	v_lshl_add_u64 v[2:3], v[0:1], 0, v[44:45]
	s_barrier
	global_load_ushort v143, v[2:3], off offset:512 nt
	v_lshl_add_u64 v[2:3], v[0:1], 0, v[46:47]
	global_load_ushort v142, v[2:3], off offset:512 nt
	v_lshl_add_u64 v[2:3], v[0:1], 0, v[48:49]
	global_load_ushort v141, v[2:3], off offset:512 nt
	v_lshl_add_u64 v[2:3], v[0:1], 0, v[50:51]
	global_load_ushort v140, v[2:3], off offset:512 nt
	v_lshl_add_u64 v[2:3], v[0:1], 0, v[52:53]
	global_load_ushort v139, v[2:3], off offset:512 nt
	v_lshl_add_u64 v[2:3], v[0:1], 0, v[54:55]
	global_load_ushort v138, v[2:3], off offset:512 nt
	v_lshl_add_u64 v[2:3], v[0:1], 0, v[56:57]
	global_load_ushort v137, v[2:3], off offset:512 nt
	v_lshl_add_u64 v[2:3], v[0:1], 0, v[58:59]
	global_load_ushort v136, v[2:3], off offset:512 nt
	v_lshl_add_u64 v[2:3], v[0:1], 0, v[60:61]
	global_load_ushort v135, v[2:3], off offset:512 nt
	v_lshl_add_u64 v[2:3], v[0:1], 0, v[62:63]
	global_load_ushort v134, v[2:3], off offset:512 nt
	v_lshl_add_u64 v[2:3], v[0:1], 0, v[64:65]
	global_load_ushort v133, v[2:3], off offset:512 nt
	v_lshl_add_u64 v[2:3], v[0:1], 0, v[66:67]
	global_load_ushort v132, v[2:3], off offset:512 nt
	v_lshl_add_u64 v[2:3], v[0:1], 0, v[68:69]
	global_load_ushort v131, v[2:3], off offset:512 nt
	v_lshl_add_u64 v[2:3], v[0:1], 0, v[70:71]
	s_lshl_b32 s16, s13, 6
	global_load_ushort v130, v[2:3], off offset:512 nt
	v_lshl_add_u64 v[2:3], v[0:1], 0, v[72:73]
	v_lshl_add_u64 v[0:1], v[0:1], 0, v[74:75]
	global_load_ushort v128, v[2:3], off offset:512 nt
	global_load_ushort v96, v[0:1], off offset:512 nt
	v_add_u32_e32 v0, s16, v119
	v_ashrrev_i32_e32 v1, 31, v0
	v_lshl_add_u64 v[0:1], v[0:1], 2, s[62:63]
	global_load_dword v129, v[0:1], off
	v_mov_b32_e32 v0, 0
	s_mov_b64 s[68:69], 0
	v_mov_b32_e32 v112, v127
	v_mov_b32_e32 v1, v0
	v_mov_b32_e32 v2, v0
	v_mov_b32_e32 v3, v0
	v_mov_b32_e32 v4, v0
	v_mov_b32_e32 v5, v0
	v_mov_b32_e32 v6, v0
	v_mov_b32_e32 v7, v0
	v_mov_b32_e32 v8, v0
	v_mov_b32_e32 v9, v0
	v_mov_b32_e32 v10, v0
	v_mov_b32_e32 v11, v0
	v_mov_b32_e32 v12, v0
	v_mov_b32_e32 v13, v0
	v_mov_b32_e32 v14, v0
	v_mov_b32_e32 v15, v0
